# plus GEMM K-loop phase transitions: s_setprio 1 hoisted above the pre-MFMA barrier, redundant lgkmcnt waits in the MFMA blocks removed, s_setprio 0 sunk below the post-MFMA barrier
# speedup vs baseline: 1.0017x; 1.0017x over previous
; #define PG8_STAGE(bufoff, gbase, voff) do { _Pragma("unroll") for (int _i = 0; _i < 2; ++_i) { \
;         const unsigned m0v_ = (unsigned)(uintptr_t)(lds + (bufoff) + ldsw + _i * 8192); \
;         asm volatile("s_mov_b32 m0, %0\n\ts_nop 0\n\tglobal_load_lds_dwordx4 %1, %2\n\ts_nop 1" :: "s"(m0v_), "v"((voff)[_i]), "s"((const char*)(gbase)) : "m0", "memory"); } } while (0)
; #define PG8_LDA(dst, b, h) do { _Pragma("unroll") for (int m = 0; m < 4; ++m) _Pragma("unroll") for (int k = 0; k < 2; ++k) dst[m][k] = *(const LAS bf16x8*)(lds + PG8_SA(b, h) + aoff + m * 2048 + k * 1024); } while (0)
; #define PG8_LDB(dst, b, h) do { _Pragma("unroll") for (int n = 0; n < 2; ++n) _Pragma("unroll") for (int k = 0; k < 2; ++k) dst[n][k] = *(const LAS bf16x8*)(lds + PG8_SB(b, h) + boff + n * 2048 + k * 1024); } while (0)
; #define PG8_MMA(ai, bj, At, Bt) do { _Pragma("unroll") for (int m = 0; m < 4; ++m) _Pragma("unroll") for (int n = 0; n < 2; ++n) _Pragma("unroll") for (int k = 0; k < 2; ++k) \
;         acc[ai][bj][m][n] = __builtin_amdgcn_mfma_f32_16x16x32_bf16(Bt[n][k], At[m][k], acc[ai][bj][m][n], 0, 0, 0); } while (0)
; #define PG8_WAIT_V(n) asm volatile("s_waitcnt vmcnt(" #n ")" ::: "memory")
; #define PG8_WAIT_L(n) asm volatile("s_waitcnt lgkmcnt(" #n ")" ::: "memory")
; template <class Prob, class Epi, class Sched>
; __device__ __forceinline__ void gemm_phase(LAS unsigned char* lds, const Prob& P, const Sched& S, const Epi& E) {
;     ...
;             const char* a1 = cA + (size_t)(t + 1) * kstep;
;             const char* a2 = last ? nA : cA + (size_t)(t + 2) * kstep; const char* b2 = last ? nB : cB + (size_t)(t + 2) * kstep;
;             const char* a3 = a2 + kstep; const char* b3 = b2 + kstep;
;             PG8_LDB(B0, 0, 0); PG8_LDB(B1, 0, 1); PG8_SCHED; PG8_LDA(At, 0, 0); PG8_STAGE(PG8_SA(1, 1), a1 + hstepA, voffA);
;             PG8_WAIT_V(8); PG8_WAIT_L(0); PG8_BAR; __builtin_amdgcn_s_setprio(1); PG8_MMA(0, 0, At, B0); PG8_MMA(0, 1, At, B1); __builtin_amdgcn_s_setprio(0); PG8_BAR; PG8_SCHED;
;             PG8_LDA(At, 0, 1); PG8_STAGE(PG8_SB(0, 0), b2, voffB); PG8_STAGE(PG8_SB(0, 1), b2 + hstepB, voffB); PG8_STAGE(PG8_SA(0, 0), a2, voffA);
;             PG8_WAIT_V(8); PG8_WAIT_L(0); PG8_BAR; __builtin_amdgcn_s_setprio(1); PG8_MMA(1, 0, At, B0); PG8_MMA(1, 1, At, B1); __builtin_amdgcn_s_setprio(0); PG8_BAR; PG8_SCHED;
.LBB0_270:
	ds_read_b128 v[136:139], v163
	ds_read_b128 v[140:143], v163 offset:1024
	ds_read_b128 v[144:147], v163 offset:2048
	ds_read_b128 v[148:151], v163 offset:3072
	s_waitcnt vmcnt(0)
	ds_read_b128 v[152:155], v164
	ds_read_b128 v[156:159], v164 offset:1024
	ds_read_b128 v[170:173], v164 offset:2048
	ds_read_b128 v[174:177], v164 offset:3072
	s_cmp_eq_u32 s71, 28
	s_cselect_b32 s68, s46, s15
	s_cselect_b32 s69, s47, s43
	s_cselect_b32 s54, s48, s45
	s_cselect_b32 s55, s49, s70
	s_add_u32 s6, s68, 0x80
	s_addc_u32 s7, s69, 0
	ds_read_b128 v[178:181], v165
	ds_read_b128 v[182:185], v165 offset:1024
	ds_read_b128 v[186:189], v165 offset:2048
	ds_read_b128 v[190:193], v165 offset:3072
	ds_read_b128 v[194:197], v165 offset:4096
	ds_read_b128 v[198:201], v165 offset:5120
	ds_read_b128 v[202:205], v165 offset:6144
	ds_read_b128 v[206:209], v165 offset:7168
	s_sub_u32 s98, s4, 0x80000
	s_subb_u32 s99, s5, 0
	s_mov_b32 m0, s72
	s_nop 0
	global_load_lds_dwordx4 v1, s[98:99]
	s_nop 1
	s_nop 0
	s_mov_b32 m0, s73
	s_nop 0
	global_load_lds_dwordx4 v161, s[98:99]
	s_nop 1
	s_mov_b32 m0, s76
	s_nop 0
	global_load_lds_dwordx4 v1, s[4:5]
	s_nop 1
	s_nop 0
	s_mov_b32 m0, s77
	s_nop 0
	global_load_lds_dwordx4 v161, s[4:5]
	s_nop 1
	s_waitcnt vmcnt(8)
	s_waitcnt lgkmcnt(0)
	s_setprio 1
	s_barrier
	v_mfma_f32_16x16x32_bf16 v[126:129], v[136:139], v[178:181], v[126:129]
	v_mfma_f32_16x16x32_bf16 v[122:125], v[144:147], v[178:181], v[122:125]
	v_mfma_f32_16x16x32_bf16 v[110:113], v[136:139], v[186:189], v[110:113]
	v_mfma_f32_16x16x32_bf16 v[106:109], v[144:147], v[186:189], v[106:109]
	v_mfma_f32_16x16x32_bf16 v[94:97], v[136:139], v[194:197], v[94:97]
	v_mfma_f32_16x16x32_bf16 v[90:93], v[144:147], v[194:197], v[90:93]
	v_mfma_f32_16x16x32_bf16 v[78:81], v[136:139], v[202:205], v[78:81]
	v_mfma_f32_16x16x32_bf16 v[74:77], v[144:147], v[202:205], v[74:77]
	v_mfma_f32_16x16x32_bf16 v[118:121], v[152:155], v[178:181], v[118:121]
	v_mfma_f32_16x16x32_bf16 v[114:117], v[170:173], v[178:181], v[114:117]
	v_mfma_f32_16x16x32_bf16 v[102:105], v[152:155], v[186:189], v[102:105]
	v_mfma_f32_16x16x32_bf16 v[98:101], v[170:173], v[186:189], v[98:101]
	v_mfma_f32_16x16x32_bf16 v[86:89], v[152:155], v[194:197], v[86:89]
	v_mfma_f32_16x16x32_bf16 v[82:85], v[170:173], v[194:197], v[82:85]
	v_mfma_f32_16x16x32_bf16 v[70:73], v[152:155], v[202:205], v[70:73]
	v_mfma_f32_16x16x32_bf16 v[66:69], v[170:173], v[202:205], v[66:69]
	v_mfma_f32_16x16x32_bf16 v[126:129], v[140:143], v[182:185], v[126:129]
	v_mfma_f32_16x16x32_bf16 v[122:125], v[148:151], v[182:185], v[122:125]
	v_mfma_f32_16x16x32_bf16 v[110:113], v[140:143], v[190:193], v[110:113]
	v_mfma_f32_16x16x32_bf16 v[106:109], v[148:151], v[190:193], v[106:109]
	v_mfma_f32_16x16x32_bf16 v[94:97], v[140:143], v[198:201], v[94:97]
	v_mfma_f32_16x16x32_bf16 v[90:93], v[148:151], v[198:201], v[90:93]
	v_mfma_f32_16x16x32_bf16 v[78:81], v[140:143], v[206:209], v[78:81]
	v_mfma_f32_16x16x32_bf16 v[74:77], v[148:151], v[206:209], v[74:77]
	v_mfma_f32_16x16x32_bf16 v[118:121], v[156:159], v[182:185], v[118:121]
	v_mfma_f32_16x16x32_bf16 v[114:117], v[174:177], v[182:185], v[114:117]
	v_mfma_f32_16x16x32_bf16 v[102:105], v[156:159], v[190:193], v[102:105]
	v_mfma_f32_16x16x32_bf16 v[98:101], v[174:177], v[190:193], v[98:101]
	v_mfma_f32_16x16x32_bf16 v[86:89], v[156:159], v[198:201], v[86:89]
	v_mfma_f32_16x16x32_bf16 v[82:85], v[174:177], v[198:201], v[82:85]
	v_mfma_f32_16x16x32_bf16 v[70:73], v[156:159], v[206:209], v[70:73]
	v_mfma_f32_16x16x32_bf16 v[66:69], v[174:177], v[206:209], v[66:69]
	s_barrier
	s_setprio 0
	ds_read_b128 v[178:181], v165 offset:16384
	ds_read_b128 v[182:185], v165 offset:17408
	ds_read_b128 v[186:189], v165 offset:18432
	ds_read_b128 v[190:193], v165 offset:19456
	ds_read_b128 v[194:197], v165 offset:20480
	ds_read_b128 v[198:201], v165 offset:21504
	ds_read_b128 v[202:205], v165 offset:22528
	ds_read_b128 v[206:209], v165 offset:23552
	s_mov_b32 m0, s34
	s_nop 0
	global_load_lds_dwordx4 v160, s[54:55]
	s_nop 1
	s_add_u32 s82, s54, 0x80000
	s_mov_b32 m0, s35
	s_nop 0
	global_load_lds_dwordx4 v162, s[54:55]
	s_nop 1
	s_addc_u32 s83, s55, 0
	s_mov_b32 m0, s53
	s_nop 0
	global_load_lds_dwordx4 v160, s[82:83]
	s_nop 1
	s_nop 0
	s_mov_b32 m0, s56
	s_nop 0
	global_load_lds_dwordx4 v162, s[82:83]
	s_nop 1
	s_nop 0
	s_waitcnt vmcnt(6)
	s_waitcnt lgkmcnt(0)
	s_setprio 1
	s_barrier
	v_mfma_f32_16x16x32_bf16 v[62:65], v[136:139], v[178:181], v[62:65]
	v_mfma_f32_16x16x32_bf16 v[58:61], v[144:147], v[178:181], v[58:61]
	v_mfma_f32_16x16x32_bf16 v[46:49], v[136:139], v[186:189], v[46:49]
	v_mfma_f32_16x16x32_bf16 v[42:45], v[144:147], v[186:189], v[42:45]
	v_mfma_f32_16x16x32_bf16 v[30:33], v[136:139], v[194:197], v[30:33]
	v_mfma_f32_16x16x32_bf16 v[26:29], v[144:147], v[194:197], v[26:29]
	v_mfma_f32_16x16x32_bf16 v[14:17], v[136:139], v[202:205], v[14:17]
	v_mfma_f32_16x16x32_bf16 v[10:13], v[144:147], v[202:205], v[10:13]
	v_mfma_f32_16x16x32_bf16 v[54:57], v[152:155], v[178:181], v[54:57]
	v_mfma_f32_16x16x32_bf16 v[50:53], v[170:173], v[178:181], v[50:53]
	v_mfma_f32_16x16x32_bf16 v[38:41], v[152:155], v[186:189], v[38:41]
	v_mfma_f32_16x16x32_bf16 v[34:37], v[170:173], v[186:189], v[34:37]
	v_mfma_f32_16x16x32_bf16 v[22:25], v[152:155], v[194:197], v[22:25]
	v_mfma_f32_16x16x32_bf16 v[18:21], v[170:173], v[194:197], v[18:21]
	v_mfma_f32_16x16x32_bf16 v[6:9], v[152:155], v[202:205], v[6:9]
	v_mfma_f32_16x16x32_bf16 v[2:5], v[170:173], v[202:205], v[2:5]
	v_mfma_f32_16x16x32_bf16 v[62:65], v[140:143], v[182:185], v[62:65]
	v_mfma_f32_16x16x32_bf16 v[58:61], v[148:151], v[182:185], v[58:61]
	v_mfma_f32_16x16x32_bf16 v[46:49], v[140:143], v[190:193], v[46:49]
	v_mfma_f32_16x16x32_bf16 v[42:45], v[148:151], v[190:193], v[42:45]
	v_mfma_f32_16x16x32_bf16 v[30:33], v[140:143], v[198:201], v[30:33]
	v_mfma_f32_16x16x32_bf16 v[26:29], v[148:151], v[198:201], v[26:29]
	v_mfma_f32_16x16x32_bf16 v[14:17], v[140:143], v[206:209], v[14:17]
	v_mfma_f32_16x16x32_bf16 v[10:13], v[148:151], v[206:209], v[10:13]
	v_mfma_f32_16x16x32_bf16 v[54:57], v[156:159], v[182:185], v[54:57]
	v_mfma_f32_16x16x32_bf16 v[50:53], v[174:177], v[182:185], v[50:53]
	v_mfma_f32_16x16x32_bf16 v[38:41], v[156:159], v[190:193], v[38:41]
	v_mfma_f32_16x16x32_bf16 v[34:37], v[174:177], v[190:193], v[34:37]
	v_mfma_f32_16x16x32_bf16 v[22:25], v[156:159], v[198:201], v[22:25]
	v_mfma_f32_16x16x32_bf16 v[18:21], v[174:177], v[198:201], v[18:21]
	v_mfma_f32_16x16x32_bf16 v[6:9], v[156:159], v[206:209], v[6:9]
	v_mfma_f32_16x16x32_bf16 v[2:5], v[174:177], v[206:209], v[2:5]
	s_barrier
; #define PG8_STAGE(bufoff, gbase, voff) do { _Pragma("unroll") for (int _i = 0; _i < 2; ++_i) { \
;         const unsigned m0v_ = (unsigned)(uintptr_t)(lds + (bufoff) + ldsw + _i * 8192); \
;         asm volatile("s_mov_b32 m0, %0\n\ts_nop 0\n\tglobal_load_lds_dwordx4 %1, %2\n\ts_nop 1" :: "s"(m0v_), "v"((voff)[_i]), "s"((const char*)(gbase)) : "m0", "memory"); } } while (0)
; #define PG8_LDA(dst, b, h) do { _Pragma("unroll") for (int m = 0; m < 4; ++m) _Pragma("unroll") for (int k = 0; k < 2; ++k) dst[m][k] = *(const LAS bf16x8*)(lds + PG8_SA(b, h) + aoff + m * 2048 + k * 1024); } while (0)
; #define PG8_LDB(dst, b, h) do { _Pragma("unroll") for (int n = 0; n < 2; ++n) _Pragma("unroll") for (int k = 0; k < 2; ++k) dst[n][k] = *(const LAS bf16x8*)(lds + PG8_SB(b, h) + boff + n * 2048 + k * 1024); } while (0)
; #define PG8_MMA(ai, bj, At, Bt) do { _Pragma("unroll") for (int m = 0; m < 4; ++m) _Pragma("unroll") for (int n = 0; n < 2; ++n) _Pragma("unroll") for (int k = 0; k < 2; ++k) \
;         acc[ai][bj][m][n] = __builtin_amdgcn_mfma_f32_16x16x32_bf16(Bt[n][k], At[m][k], acc[ai][bj][m][n], 0, 0, 0); } while (0)
; #define PG8_WAIT_V(n) asm volatile("s_waitcnt vmcnt(" #n ")" ::: "memory")
; #define PG8_WAIT_L(n) asm volatile("s_waitcnt lgkmcnt(" #n ")" ::: "memory")
; #define PG8_BAR __builtin_amdgcn_s_barrier()
; #define PG8_SCHED __builtin_amdgcn_sched_barrier(0)
; template <class Prob, class Epi, class Sched>
; __device__ __forceinline__ void gemm_phase(LAS unsigned char* lds, const Prob& P, const Sched& S, const Epi& E) {
;     ...
;             PG8_LDB(B0, 1, 0); PG8_LDB(B1, 1, 1); PG8_SCHED; PG8_LDA(At, 1, 0); PG8_STAGE(PG8_SA(0, 1), a2 + hstepA, voffA);
;             PG8_WAIT_V(8); PG8_WAIT_L(0); PG8_BAR; __builtin_amdgcn_s_setprio(1); PG8_MMA(0, 0, At, B0); PG8_MMA(0, 1, At, B1); __builtin_amdgcn_s_setprio(0); PG8_BAR; PG8_SCHED;
;             PG8_LDA(At, 1, 1); PG8_STAGE(PG8_SB(1, 0), b3, voffB); PG8_STAGE(PG8_SB(1, 1), b3 + hstepB, voffB); PG8_STAGE(PG8_SA(1, 0), a3, voffA);
;             PG8_WAIT_V(8); PG8_WAIT_L(0); PG8_BAR; __builtin_amdgcn_s_setprio(1); PG8_MMA(1, 0, At, B0); PG8_MMA(1, 1, At, B1); __builtin_amdgcn_s_setprio(0); PG8_BAR; PG8_SCHED;
;         }
;         if (wr == 0) PG8_BAR;
	s_setprio 0
	ds_read_b128 v[136:139], v166
	ds_read_b128 v[140:143], v166 offset:1024
	ds_read_b128 v[144:147], v166 offset:2048
	ds_read_b128 v[148:151], v166 offset:3072
	ds_read_b128 v[152:155], v167
	ds_read_b128 v[156:159], v167 offset:1024
	ds_read_b128 v[170:173], v167 offset:2048
	ds_read_b128 v[174:177], v167 offset:3072
	ds_read_b128 v[178:181], v165 offset:32768
	ds_read_b128 v[182:185], v165 offset:33792
	ds_read_b128 v[186:189], v165 offset:34816
	ds_read_b128 v[190:193], v165 offset:35840
	ds_read_b128 v[194:197], v165 offset:36864
	ds_read_b128 v[198:201], v165 offset:37888
	ds_read_b128 v[202:205], v165 offset:38912
	ds_read_b128 v[206:209], v165 offset:39936
	s_mov_b32 m0, s3
	s_nop 0
	global_load_lds_dwordx4 v1, s[68:69]
	s_nop 1
	s_nop 0
	s_mov_b32 m0, s57
	s_nop 0
	global_load_lds_dwordx4 v161, s[68:69]
	s_nop 1
	s_add_u32 s68, s68, 0x80000
	s_addc_u32 s69, s69, 0
	s_mov_b32 m0, s58
	s_nop 0
	global_load_lds_dwordx4 v1, s[68:69]
	s_nop 1
	s_nop 0
	s_mov_b32 m0, s59
	s_nop 0
	global_load_lds_dwordx4 v161, s[68:69]
	s_nop 1
	s_waitcnt vmcnt(8)
	s_waitcnt lgkmcnt(0)
	s_setprio 1
	s_barrier
	v_mfma_f32_16x16x32_bf16 v[126:129], v[136:139], v[178:181], v[126:129]
	v_mfma_f32_16x16x32_bf16 v[122:125], v[144:147], v[178:181], v[122:125]
	v_mfma_f32_16x16x32_bf16 v[110:113], v[136:139], v[186:189], v[110:113]
	v_mfma_f32_16x16x32_bf16 v[106:109], v[144:147], v[186:189], v[106:109]
	v_mfma_f32_16x16x32_bf16 v[94:97], v[136:139], v[194:197], v[94:97]
	v_mfma_f32_16x16x32_bf16 v[90:93], v[144:147], v[194:197], v[90:93]
	v_mfma_f32_16x16x32_bf16 v[78:81], v[136:139], v[202:205], v[78:81]
	v_mfma_f32_16x16x32_bf16 v[74:77], v[144:147], v[202:205], v[74:77]
	v_mfma_f32_16x16x32_bf16 v[118:121], v[152:155], v[178:181], v[118:121]
	v_mfma_f32_16x16x32_bf16 v[114:117], v[170:173], v[178:181], v[114:117]
	v_mfma_f32_16x16x32_bf16 v[102:105], v[152:155], v[186:189], v[102:105]
	v_mfma_f32_16x16x32_bf16 v[98:101], v[170:173], v[186:189], v[98:101]
	v_mfma_f32_16x16x32_bf16 v[86:89], v[152:155], v[194:197], v[86:89]
	v_mfma_f32_16x16x32_bf16 v[82:85], v[170:173], v[194:197], v[82:85]
	v_mfma_f32_16x16x32_bf16 v[70:73], v[152:155], v[202:205], v[70:73]
	v_mfma_f32_16x16x32_bf16 v[66:69], v[170:173], v[202:205], v[66:69]
	v_mfma_f32_16x16x32_bf16 v[126:129], v[140:143], v[182:185], v[126:129]
	v_mfma_f32_16x16x32_bf16 v[122:125], v[148:151], v[182:185], v[122:125]
	v_mfma_f32_16x16x32_bf16 v[110:113], v[140:143], v[190:193], v[110:113]
	v_mfma_f32_16x16x32_bf16 v[106:109], v[148:151], v[190:193], v[106:109]
	v_mfma_f32_16x16x32_bf16 v[94:97], v[140:143], v[198:201], v[94:97]
	v_mfma_f32_16x16x32_bf16 v[90:93], v[148:151], v[198:201], v[90:93]
	v_mfma_f32_16x16x32_bf16 v[78:81], v[140:143], v[206:209], v[78:81]
	v_mfma_f32_16x16x32_bf16 v[74:77], v[148:151], v[206:209], v[74:77]
	v_mfma_f32_16x16x32_bf16 v[118:121], v[156:159], v[182:185], v[118:121]
	v_mfma_f32_16x16x32_bf16 v[114:117], v[174:177], v[182:185], v[114:117]
	v_mfma_f32_16x16x32_bf16 v[102:105], v[156:159], v[190:193], v[102:105]
	v_mfma_f32_16x16x32_bf16 v[98:101], v[174:177], v[190:193], v[98:101]
	v_mfma_f32_16x16x32_bf16 v[86:89], v[156:159], v[198:201], v[86:89]
	v_mfma_f32_16x16x32_bf16 v[82:85], v[174:177], v[198:201], v[82:85]
	v_mfma_f32_16x16x32_bf16 v[70:73], v[156:159], v[206:209], v[70:73]
	v_mfma_f32_16x16x32_bf16 v[66:69], v[174:177], v[206:209], v[66:69]
	s_barrier
	s_setprio 0
	ds_read_b128 v[178:181], v165 offset:49152
	ds_read_b128 v[182:185], v165 offset:50176
	ds_read_b128 v[186:189], v165 offset:51200
	ds_read_b128 v[190:193], v165 offset:52224
	ds_read_b128 v[194:197], v165 offset:53248
	ds_read_b128 v[198:201], v165 offset:54272
	ds_read_b128 v[202:205], v165 offset:55296
	ds_read_b128 v[206:209], v165 offset:56320
	s_add_u32 s68, s54, 0x80
	s_addc_u32 s69, s55, 0
	s_mov_b32 m0, s64
	s_nop 0
	global_load_lds_dwordx4 v160, s[68:69]
	s_nop 1
	s_add_u32 s54, s54, 0x80080
	s_mov_b32 m0, s65
	s_nop 0
	global_load_lds_dwordx4 v162, s[68:69]
	s_nop 1
	s_addc_u32 s55, s55, 0
	s_mov_b32 m0, s74
	s_nop 0
	global_load_lds_dwordx4 v160, s[54:55]
	s_nop 1
	s_nop 0
	s_mov_b32 m0, s75
	s_nop 0
	global_load_lds_dwordx4 v162, s[54:55]
	s_nop 1
	s_nop 0
	s_waitcnt vmcnt(6)
	s_waitcnt lgkmcnt(0)
	s_setprio 1
	s_barrier
	v_mfma_f32_16x16x32_bf16 v[62:65], v[136:139], v[178:181], v[62:65]
	v_mfma_f32_16x16x32_bf16 v[58:61], v[144:147], v[178:181], v[58:61]
	v_mfma_f32_16x16x32_bf16 v[46:49], v[136:139], v[186:189], v[46:49]
	v_mfma_f32_16x16x32_bf16 v[42:45], v[144:147], v[186:189], v[42:45]
	v_mfma_f32_16x16x32_bf16 v[30:33], v[136:139], v[194:197], v[30:33]
	v_mfma_f32_16x16x32_bf16 v[26:29], v[144:147], v[194:197], v[26:29]
	v_mfma_f32_16x16x32_bf16 v[14:17], v[136:139], v[202:205], v[14:17]
	v_mfma_f32_16x16x32_bf16 v[10:13], v[144:147], v[202:205], v[10:13]
	v_mfma_f32_16x16x32_bf16 v[54:57], v[152:155], v[178:181], v[54:57]
	v_mfma_f32_16x16x32_bf16 v[50:53], v[170:173], v[178:181], v[50:53]
	v_mfma_f32_16x16x32_bf16 v[38:41], v[152:155], v[186:189], v[38:41]
	v_mfma_f32_16x16x32_bf16 v[34:37], v[170:173], v[186:189], v[34:37]
	v_mfma_f32_16x16x32_bf16 v[22:25], v[152:155], v[194:197], v[22:25]
	v_mfma_f32_16x16x32_bf16 v[18:21], v[170:173], v[194:197], v[18:21]
	v_mfma_f32_16x16x32_bf16 v[6:9], v[152:155], v[202:205], v[6:9]
	v_mfma_f32_16x16x32_bf16 v[2:5], v[170:173], v[202:205], v[2:5]
	v_mfma_f32_16x16x32_bf16 v[62:65], v[140:143], v[182:185], v[62:65]
	v_mfma_f32_16x16x32_bf16 v[58:61], v[148:151], v[182:185], v[58:61]
	v_mfma_f32_16x16x32_bf16 v[46:49], v[140:143], v[190:193], v[46:49]
	v_mfma_f32_16x16x32_bf16 v[42:45], v[148:151], v[190:193], v[42:45]
	v_mfma_f32_16x16x32_bf16 v[30:33], v[140:143], v[198:201], v[30:33]
	v_mfma_f32_16x16x32_bf16 v[26:29], v[148:151], v[198:201], v[26:29]
	v_mfma_f32_16x16x32_bf16 v[14:17], v[140:143], v[206:209], v[14:17]
	v_mfma_f32_16x16x32_bf16 v[10:13], v[148:151], v[206:209], v[10:13]
	v_mfma_f32_16x16x32_bf16 v[54:57], v[156:159], v[182:185], v[54:57]
	v_mfma_f32_16x16x32_bf16 v[50:53], v[174:177], v[182:185], v[50:53]
	v_mfma_f32_16x16x32_bf16 v[38:41], v[156:159], v[190:193], v[38:41]
	v_mfma_f32_16x16x32_bf16 v[34:37], v[174:177], v[190:193], v[34:37]
	v_mfma_f32_16x16x32_bf16 v[22:25], v[156:159], v[198:201], v[22:25]
	v_mfma_f32_16x16x32_bf16 v[18:21], v[174:177], v[198:201], v[18:21]
	v_mfma_f32_16x16x32_bf16 v[6:9], v[156:159], v[206:209], v[6:9]
	v_mfma_f32_16x16x32_bf16 v[2:5], v[174:177], v[206:209], v[2:5]
	s_barrier
	s_setprio 0
	s_add_i32 s71, s71, 2
	s_add_u32 s15, s15, 0x100
	s_addc_u32 s43, s43, 0
	s_add_u32 s45, s45, 0x100
	s_addc_u32 s70, s70, 0
	s_add_u32 s4, s4, 0x100
	s_addc_u32 s5, s5, 0
	s_cmp_gt_u32 s71, 29
	s_cbranch_scc0 .LBB0_270
	s_and_b64 vcc, exec, s[40:41]
	s_cbranch_vccz .LBB0_273
	s_barrier

; #define PG8_STAGE(bufoff, gbase, voff) do { _Pragma("unroll") for (int _i = 0; _i < 2; ++_i) { \
;         const unsigned m0v_ = (unsigned)(uintptr_t)(lds + (bufoff) + ldsw + _i * 8192); \
;         asm volatile("s_mov_b32 m0, %0\n\ts_nop 0\n\tglobal_load_lds_dwordx4 %1, %2\n\ts_nop 1" :: "s"(m0v_), "v"((voff)[_i]), "s"((const char*)(gbase)) : "m0", "memory"); } } while (0)
; #define PG8_LDA(dst, b, h) do { _Pragma("unroll") for (int m = 0; m < 4; ++m) _Pragma("unroll") for (int k = 0; k < 2; ++k) dst[m][k] = *(const LAS bf16x8*)(lds + PG8_SA(b, h) + aoff + m * 2048 + k * 1024); } while (0)
; #define PG8_LDB(dst, b, h) do { _Pragma("unroll") for (int n = 0; n < 2; ++n) _Pragma("unroll") for (int k = 0; k < 2; ++k) dst[n][k] = *(const LAS bf16x8*)(lds + PG8_SB(b, h) + boff + n * 2048 + k * 1024); } while (0)
; #define PG8_MMA(ai, bj, At, Bt) do { _Pragma("unroll") for (int m = 0; m < 4; ++m) _Pragma("unroll") for (int n = 0; n < 2; ++n) _Pragma("unroll") for (int k = 0; k < 2; ++k) \
;         acc[ai][bj][m][n] = __builtin_amdgcn_mfma_f32_16x16x32_bf16(Bt[n][k], At[m][k], acc[ai][bj][m][n], 0, 0, 0); } while (0)
; template <class Prob, class Epi, class Sched>
; __device__ __forceinline__ void gemm_phase(LAS unsigned char* lds, const Prob& P, const Sched& S, const Epi& E) {
;     ...
;         for (int t = 0; t < nt; t += 2) {
;             const bool last = (t == nt - 2);
;             if (Epi::MID_T >= 0) { if (t == Epi::MID_T) E.mid(acc, cur, slot, wr, wc, fr, fq, lds); }
;             const char* a1 = cA + (size_t)(t + 1) * kstep;
;             const char* a2 = last ? nA : cA + (size_t)(t + 2) * kstep; const char* b2 = last ? nB : cB + (size_t)(t + 2) * kstep;
;             const char* a3 = a2 + kstep; const char* b3 = b2 + kstep;
;             PG8_LDB(B0, 0, 0); PG8_LDB(B1, 0, 1); PG8_SCHED; PG8_LDA(At, 0, 0); PG8_STAGE(PG8_SA(1, 1), a1 + hstepA, voffA);
;             PG8_WAIT_V(8); PG8_WAIT_L(0); PG8_BAR; __builtin_amdgcn_s_setprio(1); PG8_MMA(0, 0, At, B0); PG8_MMA(0, 1, At, B1); __builtin_amdgcn_s_setprio(0); PG8_BAR; PG8_SCHED;
;             PG8_LDA(At, 0, 1); PG8_STAGE(PG8_SB(0, 0), b2, voffB); PG8_STAGE(PG8_SB(0, 1), b2 + hstepB, voffB); PG8_STAGE(PG8_SA(0, 0), a2, voffA);
;             PG8_WAIT_V(8); PG8_WAIT_L(0); PG8_BAR; __builtin_amdgcn_s_setprio(1); PG8_MMA(1, 0, At, B0); PG8_MMA(1, 1, At, B1); __builtin_amdgcn_s_setprio(0); PG8_BAR; PG8_SCHED;
.LBB0_451:
	v_add_u32_e32 v130, 0x10000, v219
	s_add_i32 s68, s6, 2
	ds_read_b128 v[132:135], v130
	s_waitcnt vmcnt(4)
	ds_read_b128 v[136:139], v130 offset:1024
	ds_read_b128 v[140:143], v130 offset:2048
	s_waitcnt vmcnt(3)
	ds_read_b128 v[144:147], v130 offset:3072
	v_add_u32_e32 v130, 0x14000, v219
	s_add_u32 s7, s78, s4
	s_waitcnt vmcnt(2)
	ds_read_b128 v[148:151], v130
	s_waitcnt vmcnt(0)
	ds_read_b128 v[152:155], v130 offset:1024
	ds_read_b128 v[156:159], v130 offset:2048
	ds_read_b128 v[160:163], v130 offset:3072
	s_addc_u32 s8, s79, s5
	s_add_u32 s9, s80, s4
	s_addc_u32 s74, s81, s5
	s_cmp_eq_u32 s55, s6
	s_cselect_b32 s10, s88, s7
	s_cselect_b32 s11, s89, s8
	s_cselect_b32 s8, s90, s9
	s_cselect_b32 s9, s91, s74
	s_add_u32 s6, s10, 0x80
	s_addc_u32 s7, s11, 0
	ds_read_b128 v[164:167], v220
	ds_read_b128 v[168:171], v220 offset:1024
	ds_read_b128 v[172:175], v220 offset:2048
	ds_read_b128 v[176:179], v220 offset:3072
	ds_read_b128 v[180:183], v220 offset:4096
	ds_read_b128 v[184:187], v220 offset:5120
	ds_read_b128 v[188:191], v220 offset:6144
	ds_read_b128 v[192:195], v220 offset:7168
	s_add_u32 s74, s49, s4
	s_addc_u32 s75, s54, s5
	s_add_u32 s74, s74, 0xffffff80
	s_addc_u32 s75, s75, -1
	s_sub_u32 s98, s74, 0x80000
	s_subb_u32 s99, s75, 0
	s_mov_b32 m0, s70
	s_nop 0
	global_load_lds_dwordx4 v1, s[98:99]
	s_nop 1
	s_nop 0
	s_mov_b32 m0, s71
	s_nop 0
	global_load_lds_dwordx4 v217, s[98:99]
	s_nop 1
	s_mov_b32 m0, s46
	s_nop 0
	global_load_lds_dwordx4 v1, s[74:75]
	s_nop 1
	s_nop 0
	s_mov_b32 m0, s47
	s_nop 0
	global_load_lds_dwordx4 v217, s[74:75]
	s_nop 1
	s_waitcnt vmcnt(8)
	s_waitcnt lgkmcnt(0)
	s_setprio 1
	s_barrier
	v_mfma_f32_16x16x32_bf16 v[2:5], v[132:135], v[164:167], v[2:5]
	v_mfma_f32_16x16x32_bf16 v[62:65], v[140:143], v[164:167], v[62:65]
	v_mfma_f32_16x16x32_bf16 v[58:61], v[132:135], v[172:175], v[58:61]
	v_mfma_f32_16x16x32_bf16 v[54:57], v[140:143], v[172:175], v[54:57]
	v_mfma_f32_16x16x32_bf16 v[50:53], v[132:135], v[180:183], v[50:53]
	v_mfma_f32_16x16x32_bf16 v[46:49], v[140:143], v[180:183], v[46:49]
	v_mfma_f32_16x16x32_bf16 v[42:45], v[132:135], v[188:191], v[42:45]
	v_mfma_f32_16x16x32_bf16 v[38:41], v[140:143], v[188:191], v[38:41]
	v_mfma_f32_16x16x32_bf16 v[34:37], v[148:151], v[164:167], v[34:37]
	v_mfma_f32_16x16x32_bf16 v[30:33], v[156:159], v[164:167], v[30:33]
	v_mfma_f32_16x16x32_bf16 v[26:29], v[148:151], v[172:175], v[26:29]
	v_mfma_f32_16x16x32_bf16 v[22:25], v[156:159], v[172:175], v[22:25]
	v_mfma_f32_16x16x32_bf16 v[18:21], v[148:151], v[180:183], v[18:21]
	v_mfma_f32_16x16x32_bf16 v[14:17], v[156:159], v[180:183], v[14:17]
	v_mfma_f32_16x16x32_bf16 v[10:13], v[148:151], v[188:191], v[10:13]
	v_mfma_f32_16x16x32_bf16 v[6:9], v[156:159], v[188:191], v[6:9]
	v_mfma_f32_16x16x32_bf16 v[2:5], v[136:139], v[168:171], v[2:5]
	v_mfma_f32_16x16x32_bf16 v[62:65], v[144:147], v[168:171], v[62:65]
	v_mfma_f32_16x16x32_bf16 v[58:61], v[136:139], v[176:179], v[58:61]
	v_mfma_f32_16x16x32_bf16 v[54:57], v[144:147], v[176:179], v[54:57]
	v_mfma_f32_16x16x32_bf16 v[50:53], v[136:139], v[184:187], v[50:53]
	v_mfma_f32_16x16x32_bf16 v[46:49], v[144:147], v[184:187], v[46:49]
	v_mfma_f32_16x16x32_bf16 v[42:45], v[136:139], v[192:195], v[42:45]
	v_mfma_f32_16x16x32_bf16 v[38:41], v[144:147], v[192:195], v[38:41]
	v_mfma_f32_16x16x32_bf16 v[34:37], v[152:155], v[168:171], v[34:37]
	v_mfma_f32_16x16x32_bf16 v[30:33], v[160:163], v[168:171], v[30:33]
	v_mfma_f32_16x16x32_bf16 v[26:29], v[152:155], v[176:179], v[26:29]
	v_mfma_f32_16x16x32_bf16 v[22:25], v[160:163], v[176:179], v[22:25]
	v_mfma_f32_16x16x32_bf16 v[18:21], v[152:155], v[184:187], v[18:21]
	v_mfma_f32_16x16x32_bf16 v[14:17], v[160:163], v[184:187], v[14:17]
	v_mfma_f32_16x16x32_bf16 v[10:13], v[152:155], v[192:195], v[10:13]
	v_mfma_f32_16x16x32_bf16 v[6:9], v[160:163], v[192:195], v[6:9]
	s_barrier
	s_setprio 0
	ds_read_b128 v[164:167], v220 offset:16384
	ds_read_b128 v[168:171], v220 offset:17408
	ds_read_b128 v[172:175], v220 offset:18432
	ds_read_b128 v[176:179], v220 offset:19456
	ds_read_b128 v[180:183], v220 offset:20480
	ds_read_b128 v[184:187], v220 offset:21504
	ds_read_b128 v[188:191], v220 offset:22528
	ds_read_b128 v[192:195], v220 offset:23552
	s_mov_b32 m0, s67
	s_nop 0
	global_load_lds_dwordx4 v216, s[8:9]
	s_nop 1
	s_add_u32 s74, s8, 0x80000
	s_mov_b32 m0, s0
	s_nop 0
	global_load_lds_dwordx4 v218, s[8:9]
	s_nop 1
	s_addc_u32 s75, s9, 0
	s_mov_b32 m0, s1
	s_nop 0
	global_load_lds_dwordx4 v216, s[74:75]
	s_nop 1
	s_nop 0
	s_mov_b32 m0, s35
	s_nop 0
	global_load_lds_dwordx4 v218, s[74:75]
	s_nop 1
	s_nop 0
	s_waitcnt vmcnt(6)
	s_waitcnt lgkmcnt(0)
	s_setprio 1
	s_barrier
; #define PG8_STAGE(bufoff, gbase, voff) do { _Pragma("unroll") for (int _i = 0; _i < 2; ++_i) { \
;         const unsigned m0v_ = (unsigned)(uintptr_t)(lds + (bufoff) + ldsw + _i * 8192); \
;         asm volatile("s_mov_b32 m0, %0\n\ts_nop 0\n\tglobal_load_lds_dwordx4 %1, %2\n\ts_nop 1" :: "s"(m0v_), "v"((voff)[_i]), "s"((const char*)(gbase)) : "m0", "memory"); } } while (0)
; #define PG8_LDA(dst, b, h) do { _Pragma("unroll") for (int m = 0; m < 4; ++m) _Pragma("unroll") for (int k = 0; k < 2; ++k) dst[m][k] = *(const LAS bf16x8*)(lds + PG8_SA(b, h) + aoff + m * 2048 + k * 1024); } while (0)
; #define PG8_LDB(dst, b, h) do { _Pragma("unroll") for (int n = 0; n < 2; ++n) _Pragma("unroll") for (int k = 0; k < 2; ++k) dst[n][k] = *(const LAS bf16x8*)(lds + PG8_SB(b, h) + boff + n * 2048 + k * 1024); } while (0)
; #define PG8_MMA(ai, bj, At, Bt) do { _Pragma("unroll") for (int m = 0; m < 4; ++m) _Pragma("unroll") for (int n = 0; n < 2; ++n) _Pragma("unroll") for (int k = 0; k < 2; ++k) \
;         acc[ai][bj][m][n] = __builtin_amdgcn_mfma_f32_16x16x32_bf16(Bt[n][k], At[m][k], acc[ai][bj][m][n], 0, 0, 0); } while (0)
; #define PG8_WAIT_V(n) asm volatile("s_waitcnt vmcnt(" #n ")" ::: "memory")
; #define PG8_WAIT_L(n) asm volatile("s_waitcnt lgkmcnt(" #n ")" ::: "memory")
; #define PG8_BAR __builtin_amdgcn_s_barrier()
; #define PG8_SCHED __builtin_amdgcn_sched_barrier(0)
; template <class Prob, class Epi, class Sched>
; __device__ __forceinline__ void gemm_phase(LAS unsigned char* lds, const Prob& P, const Sched& S, const Epi& E) {
;     ...
;             PG8_WAIT_V(8); PG8_WAIT_L(0); PG8_BAR; __builtin_amdgcn_s_setprio(1); PG8_MMA(1, 0, At, B0); PG8_MMA(1, 1, At, B1); __builtin_amdgcn_s_setprio(0); PG8_BAR; PG8_SCHED;
;             PG8_LDB(B0, 1, 0); PG8_LDB(B1, 1, 1); PG8_SCHED; PG8_LDA(At, 1, 0); PG8_STAGE(PG8_SA(0, 1), a2 + hstepA, voffA);
;             PG8_WAIT_V(8); PG8_WAIT_L(0); PG8_BAR; __builtin_amdgcn_s_setprio(1); PG8_MMA(0, 0, At, B0); PG8_MMA(0, 1, At, B1); __builtin_amdgcn_s_setprio(0); PG8_BAR; PG8_SCHED;
	v_mfma_f32_16x16x32_bf16 v[126:129], v[132:135], v[164:167], v[126:129]
	v_mfma_f32_16x16x32_bf16 v[122:125], v[140:143], v[164:167], v[122:125]
	v_mfma_f32_16x16x32_bf16 v[118:121], v[132:135], v[172:175], v[118:121]
	v_mfma_f32_16x16x32_bf16 v[114:117], v[140:143], v[172:175], v[114:117]
	v_mfma_f32_16x16x32_bf16 v[110:113], v[132:135], v[180:183], v[110:113]
	v_mfma_f32_16x16x32_bf16 v[106:109], v[140:143], v[180:183], v[106:109]
	v_mfma_f32_16x16x32_bf16 v[102:105], v[132:135], v[188:191], v[102:105]
	v_mfma_f32_16x16x32_bf16 v[98:101], v[140:143], v[188:191], v[98:101]
	v_mfma_f32_16x16x32_bf16 v[94:97], v[148:151], v[164:167], v[94:97]
	v_mfma_f32_16x16x32_bf16 v[90:93], v[156:159], v[164:167], v[90:93]
	v_mfma_f32_16x16x32_bf16 v[86:89], v[148:151], v[172:175], v[86:89]
	v_mfma_f32_16x16x32_bf16 v[82:85], v[156:159], v[172:175], v[82:85]
	v_mfma_f32_16x16x32_bf16 v[78:81], v[148:151], v[180:183], v[78:81]
	v_mfma_f32_16x16x32_bf16 v[74:77], v[156:159], v[180:183], v[74:77]
	v_mfma_f32_16x16x32_bf16 v[70:73], v[148:151], v[188:191], v[70:73]
	v_mfma_f32_16x16x32_bf16 v[66:69], v[156:159], v[188:191], v[66:69]
	v_mfma_f32_16x16x32_bf16 v[126:129], v[136:139], v[168:171], v[126:129]
	v_mfma_f32_16x16x32_bf16 v[122:125], v[144:147], v[168:171], v[122:125]
	v_mfma_f32_16x16x32_bf16 v[118:121], v[136:139], v[176:179], v[118:121]
	v_mfma_f32_16x16x32_bf16 v[114:117], v[144:147], v[176:179], v[114:117]
	v_mfma_f32_16x16x32_bf16 v[110:113], v[136:139], v[184:187], v[110:113]
	v_mfma_f32_16x16x32_bf16 v[106:109], v[144:147], v[184:187], v[106:109]
	v_mfma_f32_16x16x32_bf16 v[102:105], v[136:139], v[192:195], v[102:105]
	v_mfma_f32_16x16x32_bf16 v[98:101], v[144:147], v[192:195], v[98:101]
	v_mfma_f32_16x16x32_bf16 v[94:97], v[152:155], v[168:171], v[94:97]
	v_mfma_f32_16x16x32_bf16 v[90:93], v[160:163], v[168:171], v[90:93]
	v_mfma_f32_16x16x32_bf16 v[86:89], v[152:155], v[176:179], v[86:89]
	v_mfma_f32_16x16x32_bf16 v[82:85], v[160:163], v[176:179], v[82:85]
	v_mfma_f32_16x16x32_bf16 v[78:81], v[152:155], v[184:187], v[78:81]
	v_mfma_f32_16x16x32_bf16 v[74:77], v[160:163], v[184:187], v[74:77]
	v_mfma_f32_16x16x32_bf16 v[70:73], v[152:155], v[192:195], v[70:73]
	v_mfma_f32_16x16x32_bf16 v[66:69], v[160:163], v[192:195], v[66:69]
	s_barrier
	s_setprio 0
	v_add_u32_e32 v130, 0x18000, v219
	ds_read_b128 v[132:135], v130
	ds_read_b128 v[136:139], v130 offset:1024
	ds_read_b128 v[140:143], v130 offset:2048
	ds_read_b128 v[144:147], v130 offset:3072
	v_add_u32_e32 v130, 0x1c000, v219
	ds_read_b128 v[148:151], v130
	ds_read_b128 v[152:155], v130 offset:1024
	ds_read_b128 v[156:159], v130 offset:2048
	ds_read_b128 v[160:163], v130 offset:3072
	ds_read_b128 v[164:167], v220 offset:32768
	ds_read_b128 v[168:171], v220 offset:33792
	ds_read_b128 v[172:175], v220 offset:34816
	ds_read_b128 v[176:179], v220 offset:35840
	ds_read_b128 v[180:183], v220 offset:36864
	ds_read_b128 v[184:187], v220 offset:37888
	ds_read_b128 v[188:191], v220 offset:38912
	ds_read_b128 v[192:195], v220 offset:39936
	s_mov_b32 m0, s41
	s_nop 0
	global_load_lds_dwordx4 v1, s[10:11]
	s_nop 1
	s_nop 0
	s_mov_b32 m0, s3
	s_nop 0
	global_load_lds_dwordx4 v217, s[10:11]
	s_nop 1
	s_add_u32 s10, s10, 0x80000
	s_addc_u32 s11, s11, 0
	s_mov_b32 m0, s64
	s_nop 0
	global_load_lds_dwordx4 v1, s[10:11]
	s_nop 1
	s_nop 0
	s_mov_b32 m0, s65
	s_nop 0
	global_load_lds_dwordx4 v217, s[10:11]
	s_nop 1
	s_waitcnt vmcnt(8)
	s_waitcnt lgkmcnt(0)
	s_setprio 1
	s_barrier
; #define PG8_STAGE(bufoff, gbase, voff) do { _Pragma("unroll") for (int _i = 0; _i < 2; ++_i) { \
;         const unsigned m0v_ = (unsigned)(uintptr_t)(lds + (bufoff) + ldsw + _i * 8192); \
;         asm volatile("s_mov_b32 m0, %0\n\ts_nop 0\n\tglobal_load_lds_dwordx4 %1, %2\n\ts_nop 1" :: "s"(m0v_), "v"((voff)[_i]), "s"((const char*)(gbase)) : "m0", "memory"); } } while (0)
; #define PG8_LDA(dst, b, h) do { _Pragma("unroll") for (int m = 0; m < 4; ++m) _Pragma("unroll") for (int k = 0; k < 2; ++k) dst[m][k] = *(const LAS bf16x8*)(lds + PG8_SA(b, h) + aoff + m * 2048 + k * 1024); } while (0)
; #define PG8_MMA(ai, bj, At, Bt) do { _Pragma("unroll") for (int m = 0; m < 4; ++m) _Pragma("unroll") for (int n = 0; n < 2; ++n) _Pragma("unroll") for (int k = 0; k < 2; ++k) \
;         acc[ai][bj][m][n] = __builtin_amdgcn_mfma_f32_16x16x32_bf16(Bt[n][k], At[m][k], acc[ai][bj][m][n], 0, 0, 0); } while (0)
; #define PG8_WAIT_V(n) asm volatile("s_waitcnt vmcnt(" #n ")" ::: "memory")
; #define PG8_WAIT_L(n) asm volatile("s_waitcnt lgkmcnt(" #n ")" ::: "memory")
; #define PG8_BAR __builtin_amdgcn_s_barrier()
; #define PG8_SCHED __builtin_amdgcn_sched_barrier(0)
; template <class Prob, class Epi, class Sched>
; __device__ __forceinline__ void gemm_phase(LAS unsigned char* lds, const Prob& P, const Sched& S, const Epi& E) {
;     ...
;             PG8_WAIT_V(8); PG8_WAIT_L(0); PG8_BAR; __builtin_amdgcn_s_setprio(1); PG8_MMA(0, 0, At, B0); PG8_MMA(0, 1, At, B1); __builtin_amdgcn_s_setprio(0); PG8_BAR; PG8_SCHED;
;             PG8_LDA(At, 1, 1); PG8_STAGE(PG8_SB(1, 0), b3, voffB); PG8_STAGE(PG8_SB(1, 1), b3 + hstepB, voffB); PG8_STAGE(PG8_SA(1, 0), a3, voffA);
;             PG8_WAIT_V(8); PG8_WAIT_L(0); PG8_BAR; __builtin_amdgcn_s_setprio(1); PG8_MMA(1, 0, At, B0); PG8_MMA(1, 1, At, B1); __builtin_amdgcn_s_setprio(0); PG8_BAR; PG8_SCHED;
;         }
;         if (wr == 0) PG8_BAR;
	v_mfma_f32_16x16x32_bf16 v[2:5], v[132:135], v[164:167], v[2:5]
	v_mfma_f32_16x16x32_bf16 v[62:65], v[140:143], v[164:167], v[62:65]
	v_mfma_f32_16x16x32_bf16 v[58:61], v[132:135], v[172:175], v[58:61]
	v_mfma_f32_16x16x32_bf16 v[54:57], v[140:143], v[172:175], v[54:57]
	v_mfma_f32_16x16x32_bf16 v[50:53], v[132:135], v[180:183], v[50:53]
	v_mfma_f32_16x16x32_bf16 v[46:49], v[140:143], v[180:183], v[46:49]
	v_mfma_f32_16x16x32_bf16 v[42:45], v[132:135], v[188:191], v[42:45]
	v_mfma_f32_16x16x32_bf16 v[38:41], v[140:143], v[188:191], v[38:41]
	v_mfma_f32_16x16x32_bf16 v[34:37], v[148:151], v[164:167], v[34:37]
	v_mfma_f32_16x16x32_bf16 v[30:33], v[156:159], v[164:167], v[30:33]
	v_mfma_f32_16x16x32_bf16 v[26:29], v[148:151], v[172:175], v[26:29]
	v_mfma_f32_16x16x32_bf16 v[22:25], v[156:159], v[172:175], v[22:25]
	v_mfma_f32_16x16x32_bf16 v[18:21], v[148:151], v[180:183], v[18:21]
	v_mfma_f32_16x16x32_bf16 v[14:17], v[156:159], v[180:183], v[14:17]
	v_mfma_f32_16x16x32_bf16 v[10:13], v[148:151], v[188:191], v[10:13]
	v_mfma_f32_16x16x32_bf16 v[6:9], v[156:159], v[188:191], v[6:9]
	v_mfma_f32_16x16x32_bf16 v[2:5], v[136:139], v[168:171], v[2:5]
	v_mfma_f32_16x16x32_bf16 v[62:65], v[144:147], v[168:171], v[62:65]
	v_mfma_f32_16x16x32_bf16 v[58:61], v[136:139], v[176:179], v[58:61]
	v_mfma_f32_16x16x32_bf16 v[54:57], v[144:147], v[176:179], v[54:57]
	v_mfma_f32_16x16x32_bf16 v[50:53], v[136:139], v[184:187], v[50:53]
	v_mfma_f32_16x16x32_bf16 v[46:49], v[144:147], v[184:187], v[46:49]
	v_mfma_f32_16x16x32_bf16 v[42:45], v[136:139], v[192:195], v[42:45]
	v_mfma_f32_16x16x32_bf16 v[38:41], v[144:147], v[192:195], v[38:41]
	v_mfma_f32_16x16x32_bf16 v[34:37], v[152:155], v[168:171], v[34:37]
	v_mfma_f32_16x16x32_bf16 v[30:33], v[160:163], v[168:171], v[30:33]
	v_mfma_f32_16x16x32_bf16 v[26:29], v[152:155], v[176:179], v[26:29]
	v_mfma_f32_16x16x32_bf16 v[22:25], v[160:163], v[176:179], v[22:25]
	v_mfma_f32_16x16x32_bf16 v[18:21], v[152:155], v[184:187], v[18:21]
	v_mfma_f32_16x16x32_bf16 v[14:17], v[160:163], v[184:187], v[14:17]
	v_mfma_f32_16x16x32_bf16 v[10:13], v[152:155], v[192:195], v[10:13]
	v_mfma_f32_16x16x32_bf16 v[6:9], v[160:163], v[192:195], v[6:9]
	s_barrier
	s_setprio 0
	ds_read_b128 v[164:167], v220 offset:49152
	ds_read_b128 v[168:171], v220 offset:50176
	ds_read_b128 v[172:175], v220 offset:51200
	ds_read_b128 v[176:179], v220 offset:52224
	ds_read_b128 v[180:183], v220 offset:53248
	ds_read_b128 v[184:187], v220 offset:54272
	ds_read_b128 v[188:191], v220 offset:55296
	ds_read_b128 v[192:195], v220 offset:56320
	s_add_u32 s10, s8, 0x80
	s_addc_u32 s11, s9, 0
	s_mov_b32 m0, s62
	s_nop 0
	global_load_lds_dwordx4 v216, s[10:11]
	s_nop 1
	s_add_u32 s8, s8, 0x80080
	s_mov_b32 m0, s63
	s_nop 0
	global_load_lds_dwordx4 v218, s[10:11]
	s_nop 1
	s_addc_u32 s9, s9, 0
	s_mov_b32 m0, s44
	s_nop 0
	global_load_lds_dwordx4 v216, s[8:9]
	s_nop 1
	s_nop 0
	s_mov_b32 m0, s45
	s_nop 0
	global_load_lds_dwordx4 v218, s[8:9]
	s_nop 1
	s_nop 0
	s_waitcnt vmcnt(6)
	s_waitcnt lgkmcnt(0)
	s_setprio 1
	s_barrier
	v_mfma_f32_16x16x32_bf16 v[126:129], v[132:135], v[164:167], v[126:129]
	v_mfma_f32_16x16x32_bf16 v[122:125], v[140:143], v[164:167], v[122:125]
	v_mfma_f32_16x16x32_bf16 v[118:121], v[132:135], v[172:175], v[118:121]
	v_mfma_f32_16x16x32_bf16 v[114:117], v[140:143], v[172:175], v[114:117]
	v_mfma_f32_16x16x32_bf16 v[110:113], v[132:135], v[180:183], v[110:113]
	v_mfma_f32_16x16x32_bf16 v[106:109], v[140:143], v[180:183], v[106:109]
	v_mfma_f32_16x16x32_bf16 v[102:105], v[132:135], v[188:191], v[102:105]
	v_mfma_f32_16x16x32_bf16 v[98:101], v[140:143], v[188:191], v[98:101]
	v_mfma_f32_16x16x32_bf16 v[94:97], v[148:151], v[164:167], v[94:97]
	v_mfma_f32_16x16x32_bf16 v[90:93], v[156:159], v[164:167], v[90:93]
	v_mfma_f32_16x16x32_bf16 v[86:89], v[148:151], v[172:175], v[86:89]
	v_mfma_f32_16x16x32_bf16 v[82:85], v[156:159], v[172:175], v[82:85]
	v_mfma_f32_16x16x32_bf16 v[78:81], v[148:151], v[180:183], v[78:81]
	v_mfma_f32_16x16x32_bf16 v[74:77], v[156:159], v[180:183], v[74:77]
	v_mfma_f32_16x16x32_bf16 v[70:73], v[148:151], v[188:191], v[70:73]
	v_mfma_f32_16x16x32_bf16 v[66:69], v[156:159], v[188:191], v[66:69]
	v_mfma_f32_16x16x32_bf16 v[126:129], v[136:139], v[168:171], v[126:129]
	v_mfma_f32_16x16x32_bf16 v[122:125], v[144:147], v[168:171], v[122:125]
	v_mfma_f32_16x16x32_bf16 v[118:121], v[136:139], v[176:179], v[118:121]
	v_mfma_f32_16x16x32_bf16 v[114:117], v[144:147], v[176:179], v[114:117]
	v_mfma_f32_16x16x32_bf16 v[110:113], v[136:139], v[184:187], v[110:113]
	v_mfma_f32_16x16x32_bf16 v[106:109], v[144:147], v[184:187], v[106:109]
	v_mfma_f32_16x16x32_bf16 v[102:105], v[136:139], v[192:195], v[102:105]
	v_mfma_f32_16x16x32_bf16 v[98:101], v[144:147], v[192:195], v[98:101]
	v_mfma_f32_16x16x32_bf16 v[94:97], v[152:155], v[168:171], v[94:97]
	v_mfma_f32_16x16x32_bf16 v[90:93], v[160:163], v[168:171], v[90:93]
	v_mfma_f32_16x16x32_bf16 v[86:89], v[152:155], v[176:179], v[86:89]
	v_mfma_f32_16x16x32_bf16 v[82:85], v[160:163], v[176:179], v[82:85]
	v_mfma_f32_16x16x32_bf16 v[78:81], v[152:155], v[184:187], v[78:81]
	v_mfma_f32_16x16x32_bf16 v[74:77], v[160:163], v[184:187], v[74:77]
	v_mfma_f32_16x16x32_bf16 v[70:73], v[152:155], v[192:195], v[70:73]
	v_mfma_f32_16x16x32_bf16 v[66:69], v[160:163], v[192:195], v[66:69]
	s_barrier
	s_setprio 0
	s_add_u32 s4, s4, 0x100
	s_addc_u32 s5, s5, 0
	s_cmp_ge_i32 s68, s53
	s_mov_b32 s6, s68
	s_cbranch_scc0 .LBB0_451
	v_readlane_b32 s4, v247, 39
	v_readlane_b32 s5, v247, 40
	s_and_b64 vcc, exec, s[4:5]
	s_cbranch_vccz .LBB0_454
	s_barrier

; #define PG8_STAGE(bufoff, gbase, voff) do { _Pragma("unroll") for (int _i = 0; _i < 2; ++_i) { \
;         const unsigned m0v_ = (unsigned)(uintptr_t)(lds + (bufoff) + ldsw + _i * 8192); \
;         asm volatile("s_mov_b32 m0, %0\n\ts_nop 0\n\tglobal_load_lds_dwordx4 %1, %2\n\ts_nop 1" :: "s"(m0v_), "v"((voff)[_i]), "s"((const char*)(gbase)) : "m0", "memory"); } } while (0)
; #define PG8_LDA(dst, b, h) do { _Pragma("unroll") for (int m = 0; m < 4; ++m) _Pragma("unroll") for (int k = 0; k < 2; ++k) dst[m][k] = *(const LAS bf16x8*)(lds + PG8_SA(b, h) + aoff + m * 2048 + k * 1024); } while (0)
; #define PG8_LDB(dst, b, h) do { _Pragma("unroll") for (int n = 0; n < 2; ++n) _Pragma("unroll") for (int k = 0; k < 2; ++k) dst[n][k] = *(const LAS bf16x8*)(lds + PG8_SB(b, h) + boff + n * 2048 + k * 1024); } while (0)
; #define PG8_MMA(ai, bj, At, Bt) do { _Pragma("unroll") for (int m = 0; m < 4; ++m) _Pragma("unroll") for (int n = 0; n < 2; ++n) _Pragma("unroll") for (int k = 0; k < 2; ++k) \
;         acc[ai][bj][m][n] = __builtin_amdgcn_mfma_f32_16x16x32_bf16(Bt[n][k], At[m][k], acc[ai][bj][m][n], 0, 0, 0); } while (0)
; #define PG8_WAIT_V(n) asm volatile("s_waitcnt vmcnt(" #n ")" ::: "memory")
; #define PG8_WAIT_L(n) asm volatile("s_waitcnt lgkmcnt(" #n ")" ::: "memory")
; template <class Prob, class Epi, class Sched>
; __device__ __forceinline__ void gemm_phase(LAS unsigned char* lds, const Prob& P, const Sched& S, const Epi& E) {
;     ...
;             const char* a1 = cA + (size_t)(t + 1) * kstep;
;             const char* a2 = last ? nA : cA + (size_t)(t + 2) * kstep; const char* b2 = last ? nB : cB + (size_t)(t + 2) * kstep;
;             const char* a3 = a2 + kstep; const char* b3 = b2 + kstep;
;             PG8_LDB(B0, 0, 0); PG8_LDB(B1, 0, 1); PG8_SCHED; PG8_LDA(At, 0, 0); PG8_STAGE(PG8_SA(1, 1), a1 + hstepA, voffA);
;             PG8_WAIT_V(8); PG8_WAIT_L(0); PG8_BAR; __builtin_amdgcn_s_setprio(1); PG8_MMA(0, 0, At, B0); PG8_MMA(0, 1, At, B1); __builtin_amdgcn_s_setprio(0); PG8_BAR; PG8_SCHED;
;             PG8_LDA(At, 0, 1); PG8_STAGE(PG8_SB(0, 0), b2, voffB); PG8_STAGE(PG8_SB(0, 1), b2 + hstepB, voffB); PG8_STAGE(PG8_SA(0, 0), a2, voffA);
;             PG8_WAIT_V(8); PG8_WAIT_L(0); PG8_BAR; __builtin_amdgcn_s_setprio(1); PG8_MMA(1, 0, At, B0); PG8_MMA(1, 1, At, B1); __builtin_amdgcn_s_setprio(0); PG8_BAR; PG8_SCHED;
.LBB0_866:
	v_add_u32_e32 v130, 0x10000, v143
	ds_read_b128 v[136:139], v130
	ds_read_b128 v[148:151], v130 offset:1024
	ds_read_b128 v[152:155], v130 offset:2048
	ds_read_b128 v[156:159], v130 offset:3072
	v_add_u32_e32 v130, 0x14000, v143
	ds_read_b128 v[160:163], v130
	ds_read_b128 v[164:167], v130 offset:1024
	ds_read_b128 v[168:171], v130 offset:2048
	ds_read_b128 v[172:175], v130 offset:3072
	s_cmp_eq_u32 s83, 28
	s_cselect_b32 s64, s48, s47
	s_cselect_b32 s65, s49, s80
	s_cselect_b32 s62, s50, s81
	s_cselect_b32 s63, s51, s82
	s_add_u32 s54, s64, 0x80
	s_addc_u32 s55, s65, 0
	ds_read_b128 v[176:179], v144
	ds_read_b128 v[180:183], v144 offset:1024
	ds_read_b128 v[184:187], v144 offset:2048
	ds_read_b128 v[188:191], v144 offset:3072
	ds_read_b128 v[192:195], v144 offset:4096
	ds_read_b128 v[196:199], v144 offset:5120
	ds_read_b128 v[200:203], v144 offset:6144
	ds_read_b128 v[204:207], v144 offset:7168
	s_sub_u32 s98, s4, 0x80000
	s_subb_u32 s99, s5, 0
	s_mov_b32 m0, s69
	s_nop 0
	global_load_lds_dwordx4 v1, s[98:99]
	s_nop 1
	s_nop 0
	s_mov_b32 m0, s70
	s_nop 0
	global_load_lds_dwordx4 v141, s[98:99]
	s_nop 1
	s_mov_b32 m0, s74
	s_nop 0
	global_load_lds_dwordx4 v1, s[4:5]
	s_nop 1
	s_nop 0
	s_mov_b32 m0, s75
	s_nop 0
	global_load_lds_dwordx4 v141, s[4:5]
	s_nop 1
	s_waitcnt vmcnt(8)
	s_waitcnt lgkmcnt(0)
	s_setprio 1
	s_barrier
	v_mfma_f32_16x16x32_bf16 v[2:5], v[136:139], v[176:179], v[2:5]
	v_mfma_f32_16x16x32_bf16 v[22:25], v[152:155], v[176:179], v[22:25]
	v_mfma_f32_16x16x32_bf16 v[6:9], v[136:139], v[184:187], v[6:9]
	v_mfma_f32_16x16x32_bf16 v[26:29], v[152:155], v[184:187], v[26:29]
	v_mfma_f32_16x16x32_bf16 v[14:17], v[136:139], v[192:195], v[14:17]
	v_mfma_f32_16x16x32_bf16 v[42:45], v[152:155], v[192:195], v[42:45]
	v_mfma_f32_16x16x32_bf16 v[34:37], v[136:139], v[200:203], v[34:37]
	v_mfma_f32_16x16x32_bf16 v[54:57], v[152:155], v[200:203], v[54:57]
	v_mfma_f32_16x16x32_bf16 v[10:13], v[160:163], v[176:179], v[10:13]
	v_mfma_f32_16x16x32_bf16 v[30:33], v[168:171], v[176:179], v[30:33]
	v_mfma_f32_16x16x32_bf16 v[18:21], v[160:163], v[184:187], v[18:21]
	v_mfma_f32_16x16x32_bf16 v[46:49], v[168:171], v[184:187], v[46:49]
	v_mfma_f32_16x16x32_bf16 v[38:41], v[160:163], v[192:195], v[38:41]
	v_mfma_f32_16x16x32_bf16 v[58:61], v[168:171], v[192:195], v[58:61]
	v_mfma_f32_16x16x32_bf16 v[50:53], v[160:163], v[200:203], v[50:53]
	v_mfma_f32_16x16x32_bf16 v[66:69], v[168:171], v[200:203], v[66:69]
	v_mfma_f32_16x16x32_bf16 v[2:5], v[148:151], v[180:183], v[2:5]
	v_mfma_f32_16x16x32_bf16 v[22:25], v[156:159], v[180:183], v[22:25]
	v_mfma_f32_16x16x32_bf16 v[6:9], v[148:151], v[188:191], v[6:9]
	v_mfma_f32_16x16x32_bf16 v[26:29], v[156:159], v[188:191], v[26:29]
	v_mfma_f32_16x16x32_bf16 v[14:17], v[148:151], v[196:199], v[14:17]
	v_mfma_f32_16x16x32_bf16 v[42:45], v[156:159], v[196:199], v[42:45]
	v_mfma_f32_16x16x32_bf16 v[34:37], v[148:151], v[204:207], v[34:37]
	v_mfma_f32_16x16x32_bf16 v[54:57], v[156:159], v[204:207], v[54:57]
	v_mfma_f32_16x16x32_bf16 v[10:13], v[164:167], v[180:183], v[10:13]
	v_mfma_f32_16x16x32_bf16 v[30:33], v[172:175], v[180:183], v[30:33]
	v_mfma_f32_16x16x32_bf16 v[18:21], v[164:167], v[188:191], v[18:21]
	v_mfma_f32_16x16x32_bf16 v[46:49], v[172:175], v[188:191], v[46:49]
	v_mfma_f32_16x16x32_bf16 v[38:41], v[164:167], v[196:199], v[38:41]
	v_mfma_f32_16x16x32_bf16 v[58:61], v[172:175], v[196:199], v[58:61]
	v_mfma_f32_16x16x32_bf16 v[50:53], v[164:167], v[204:207], v[50:53]
	v_mfma_f32_16x16x32_bf16 v[66:69], v[172:175], v[204:207], v[66:69]
	s_barrier
	s_setprio 0
	ds_read_b128 v[176:179], v144 offset:16384
	ds_read_b128 v[180:183], v144 offset:17408
	ds_read_b128 v[184:187], v144 offset:18432
	ds_read_b128 v[188:191], v144 offset:19456
	ds_read_b128 v[192:195], v144 offset:20480
	ds_read_b128 v[196:199], v144 offset:21504
	ds_read_b128 v[200:203], v144 offset:22528
	ds_read_b128 v[204:207], v144 offset:23552
	s_mov_b32 m0, s41
	s_nop 0
	global_load_lds_dwordx4 v140, s[62:63]
	s_nop 1
	s_add_u32 s84, s62, 0x80000
	s_mov_b32 m0, s53
	s_nop 0
	global_load_lds_dwordx4 v142, s[62:63]
	s_nop 1
	s_addc_u32 s85, s63, 0
	s_mov_b32 m0, s56
	s_nop 0
	global_load_lds_dwordx4 v140, s[84:85]
	s_nop 1
	s_nop 0
	s_mov_b32 m0, s57
	s_nop 0
	global_load_lds_dwordx4 v142, s[84:85]
	s_nop 1
	s_nop 0
	s_waitcnt vmcnt(6)
	s_waitcnt lgkmcnt(0)
	s_setprio 1
	s_barrier
	v_mfma_f32_16x16x32_bf16 v[62:65], v[136:139], v[176:179], v[62:65]
	v_mfma_f32_16x16x32_bf16 v[78:81], v[152:155], v[176:179], v[78:81]
	v_mfma_f32_16x16x32_bf16 v[70:73], v[136:139], v[184:187], v[70:73]
	v_mfma_f32_16x16x32_bf16 v[90:93], v[152:155], v[184:187], v[90:93]
	v_mfma_f32_16x16x32_bf16 v[82:85], v[136:139], v[192:195], v[82:85]
	v_mfma_f32_16x16x32_bf16 v[106:109], v[152:155], v[192:195], v[106:109]
	v_mfma_f32_16x16x32_bf16 v[98:101], v[136:139], v[200:203], v[98:101]
	v_mfma_f32_16x16x32_bf16 v[118:121], v[152:155], v[200:203], v[118:121]
	v_mfma_f32_16x16x32_bf16 v[74:77], v[160:163], v[176:179], v[74:77]
	v_mfma_f32_16x16x32_bf16 v[94:97], v[168:171], v[176:179], v[94:97]
	v_mfma_f32_16x16x32_bf16 v[86:89], v[160:163], v[184:187], v[86:89]
	v_mfma_f32_16x16x32_bf16 v[110:113], v[168:171], v[184:187], v[110:113]
	v_mfma_f32_16x16x32_bf16 v[102:105], v[160:163], v[192:195], v[102:105]
	v_mfma_f32_16x16x32_bf16 v[122:125], v[168:171], v[192:195], v[122:125]
	v_mfma_f32_16x16x32_bf16 v[114:117], v[160:163], v[200:203], v[114:117]
	v_mfma_f32_16x16x32_bf16 v[126:129], v[168:171], v[200:203], v[126:129]
	v_mfma_f32_16x16x32_bf16 v[62:65], v[148:151], v[180:183], v[62:65]
	v_mfma_f32_16x16x32_bf16 v[78:81], v[156:159], v[180:183], v[78:81]
	v_mfma_f32_16x16x32_bf16 v[70:73], v[148:151], v[188:191], v[70:73]
	v_mfma_f32_16x16x32_bf16 v[90:93], v[156:159], v[188:191], v[90:93]
	v_mfma_f32_16x16x32_bf16 v[82:85], v[148:151], v[196:199], v[82:85]
	v_mfma_f32_16x16x32_bf16 v[106:109], v[156:159], v[196:199], v[106:109]
	v_mfma_f32_16x16x32_bf16 v[98:101], v[148:151], v[204:207], v[98:101]
	v_mfma_f32_16x16x32_bf16 v[118:121], v[156:159], v[204:207], v[118:121]
	v_mfma_f32_16x16x32_bf16 v[74:77], v[164:167], v[180:183], v[74:77]
	v_mfma_f32_16x16x32_bf16 v[94:97], v[172:175], v[180:183], v[94:97]
	v_mfma_f32_16x16x32_bf16 v[86:89], v[164:167], v[188:191], v[86:89]
	v_mfma_f32_16x16x32_bf16 v[110:113], v[172:175], v[188:191], v[110:113]
	v_mfma_f32_16x16x32_bf16 v[102:105], v[164:167], v[196:199], v[102:105]
	v_mfma_f32_16x16x32_bf16 v[122:125], v[172:175], v[196:199], v[122:125]
	v_mfma_f32_16x16x32_bf16 v[114:117], v[164:167], v[204:207], v[114:117]
	v_mfma_f32_16x16x32_bf16 v[126:129], v[172:175], v[204:207], v[126:129]
	s_barrier
; #define PG8_STAGE(bufoff, gbase, voff) do { _Pragma("unroll") for (int _i = 0; _i < 2; ++_i) { \
;         const unsigned m0v_ = (unsigned)(uintptr_t)(lds + (bufoff) + ldsw + _i * 8192); \
;         asm volatile("s_mov_b32 m0, %0\n\ts_nop 0\n\tglobal_load_lds_dwordx4 %1, %2\n\ts_nop 1" :: "s"(m0v_), "v"((voff)[_i]), "s"((const char*)(gbase)) : "m0", "memory"); } } while (0)
; #define PG8_LDA(dst, b, h) do { _Pragma("unroll") for (int m = 0; m < 4; ++m) _Pragma("unroll") for (int k = 0; k < 2; ++k) dst[m][k] = *(const LAS bf16x8*)(lds + PG8_SA(b, h) + aoff + m * 2048 + k * 1024); } while (0)
; #define PG8_LDB(dst, b, h) do { _Pragma("unroll") for (int n = 0; n < 2; ++n) _Pragma("unroll") for (int k = 0; k < 2; ++k) dst[n][k] = *(const LAS bf16x8*)(lds + PG8_SB(b, h) + boff + n * 2048 + k * 1024); } while (0)
; #define PG8_MMA(ai, bj, At, Bt) do { _Pragma("unroll") for (int m = 0; m < 4; ++m) _Pragma("unroll") for (int n = 0; n < 2; ++n) _Pragma("unroll") for (int k = 0; k < 2; ++k) \
;         acc[ai][bj][m][n] = __builtin_amdgcn_mfma_f32_16x16x32_bf16(Bt[n][k], At[m][k], acc[ai][bj][m][n], 0, 0, 0); } while (0)
; #define PG8_WAIT_V(n) asm volatile("s_waitcnt vmcnt(" #n ")" ::: "memory")
; #define PG8_WAIT_L(n) asm volatile("s_waitcnt lgkmcnt(" #n ")" ::: "memory")
; #define PG8_BAR __builtin_amdgcn_s_barrier()
; #define PG8_SCHED __builtin_amdgcn_sched_barrier(0)
; template <class Prob, class Epi, class Sched>
; __device__ __forceinline__ void gemm_phase(LAS unsigned char* lds, const Prob& P, const Sched& S, const Epi& E) {
;     ...
;             PG8_LDB(B0, 1, 0); PG8_LDB(B1, 1, 1); PG8_SCHED; PG8_LDA(At, 1, 0); PG8_STAGE(PG8_SA(0, 1), a2 + hstepA, voffA);
;             PG8_WAIT_V(8); PG8_WAIT_L(0); PG8_BAR; __builtin_amdgcn_s_setprio(1); PG8_MMA(0, 0, At, B0); PG8_MMA(0, 1, At, B1); __builtin_amdgcn_s_setprio(0); PG8_BAR; PG8_SCHED;
;             PG8_LDA(At, 1, 1); PG8_STAGE(PG8_SB(1, 0), b3, voffB); PG8_STAGE(PG8_SB(1, 1), b3 + hstepB, voffB); PG8_STAGE(PG8_SA(1, 0), a3, voffA);
;             PG8_WAIT_V(8); PG8_WAIT_L(0); PG8_BAR; __builtin_amdgcn_s_setprio(1); PG8_MMA(1, 0, At, B0); PG8_MMA(1, 1, At, B1); __builtin_amdgcn_s_setprio(0); PG8_BAR; PG8_SCHED;
;         }
	s_setprio 0
	v_add_u32_e32 v130, 0x18000, v143
	ds_read_b128 v[136:139], v130
	ds_read_b128 v[148:151], v130 offset:1024
	ds_read_b128 v[152:155], v130 offset:2048
	ds_read_b128 v[156:159], v130 offset:3072
	v_add_u32_e32 v130, 0x1c000, v143
	ds_read_b128 v[160:163], v130
	ds_read_b128 v[164:167], v130 offset:1024
	ds_read_b128 v[168:171], v130 offset:2048
	ds_read_b128 v[172:175], v130 offset:3072
	ds_read_b128 v[176:179], v144 offset:32768
	ds_read_b128 v[180:183], v144 offset:33792
	ds_read_b128 v[184:187], v144 offset:34816
	ds_read_b128 v[188:191], v144 offset:35840
	ds_read_b128 v[192:195], v144 offset:36864
	ds_read_b128 v[196:199], v144 offset:37888
	ds_read_b128 v[200:203], v144 offset:38912
	ds_read_b128 v[204:207], v144 offset:39936
	s_mov_b32 m0, s34
	s_nop 0
	global_load_lds_dwordx4 v1, s[64:65]
	s_nop 1
	s_nop 0
	s_mov_b32 m0, s58
	s_nop 0
	global_load_lds_dwordx4 v141, s[64:65]
	s_nop 1
	s_add_u32 s64, s64, 0x80000
	s_addc_u32 s65, s65, 0
	s_mov_b32 m0, s59
	s_nop 0
	global_load_lds_dwordx4 v1, s[64:65]
	s_nop 1
	s_nop 0
	s_mov_b32 m0, s60
	s_nop 0
	global_load_lds_dwordx4 v141, s[64:65]
	s_nop 1
	s_waitcnt vmcnt(8)
	s_waitcnt lgkmcnt(0)
	s_setprio 1
	s_barrier
	v_mfma_f32_16x16x32_bf16 v[2:5], v[136:139], v[176:179], v[2:5]
	v_mfma_f32_16x16x32_bf16 v[22:25], v[152:155], v[176:179], v[22:25]
	v_mfma_f32_16x16x32_bf16 v[6:9], v[136:139], v[184:187], v[6:9]
	v_mfma_f32_16x16x32_bf16 v[26:29], v[152:155], v[184:187], v[26:29]
	v_mfma_f32_16x16x32_bf16 v[14:17], v[136:139], v[192:195], v[14:17]
	v_mfma_f32_16x16x32_bf16 v[42:45], v[152:155], v[192:195], v[42:45]
	v_mfma_f32_16x16x32_bf16 v[34:37], v[136:139], v[200:203], v[34:37]
	v_mfma_f32_16x16x32_bf16 v[54:57], v[152:155], v[200:203], v[54:57]
	v_mfma_f32_16x16x32_bf16 v[10:13], v[160:163], v[176:179], v[10:13]
	v_mfma_f32_16x16x32_bf16 v[30:33], v[168:171], v[176:179], v[30:33]
	v_mfma_f32_16x16x32_bf16 v[18:21], v[160:163], v[184:187], v[18:21]
	v_mfma_f32_16x16x32_bf16 v[46:49], v[168:171], v[184:187], v[46:49]
	v_mfma_f32_16x16x32_bf16 v[38:41], v[160:163], v[192:195], v[38:41]
	v_mfma_f32_16x16x32_bf16 v[58:61], v[168:171], v[192:195], v[58:61]
	v_mfma_f32_16x16x32_bf16 v[50:53], v[160:163], v[200:203], v[50:53]
	v_mfma_f32_16x16x32_bf16 v[66:69], v[168:171], v[200:203], v[66:69]
	v_mfma_f32_16x16x32_bf16 v[2:5], v[148:151], v[180:183], v[2:5]
	v_mfma_f32_16x16x32_bf16 v[22:25], v[156:159], v[180:183], v[22:25]
	v_mfma_f32_16x16x32_bf16 v[6:9], v[148:151], v[188:191], v[6:9]
	v_mfma_f32_16x16x32_bf16 v[26:29], v[156:159], v[188:191], v[26:29]
	v_mfma_f32_16x16x32_bf16 v[14:17], v[148:151], v[196:199], v[14:17]
	v_mfma_f32_16x16x32_bf16 v[42:45], v[156:159], v[196:199], v[42:45]
	v_mfma_f32_16x16x32_bf16 v[34:37], v[148:151], v[204:207], v[34:37]
	v_mfma_f32_16x16x32_bf16 v[54:57], v[156:159], v[204:207], v[54:57]
	v_mfma_f32_16x16x32_bf16 v[10:13], v[164:167], v[180:183], v[10:13]
	v_mfma_f32_16x16x32_bf16 v[30:33], v[172:175], v[180:183], v[30:33]
	v_mfma_f32_16x16x32_bf16 v[18:21], v[164:167], v[188:191], v[18:21]
	v_mfma_f32_16x16x32_bf16 v[46:49], v[172:175], v[188:191], v[46:49]
	v_mfma_f32_16x16x32_bf16 v[38:41], v[164:167], v[196:199], v[38:41]
	v_mfma_f32_16x16x32_bf16 v[58:61], v[172:175], v[196:199], v[58:61]
	v_mfma_f32_16x16x32_bf16 v[50:53], v[164:167], v[204:207], v[50:53]
	v_mfma_f32_16x16x32_bf16 v[66:69], v[172:175], v[204:207], v[66:69]
	s_barrier
	s_setprio 0
	ds_read_b128 v[176:179], v144 offset:49152
	ds_read_b128 v[180:183], v144 offset:50176
	ds_read_b128 v[184:187], v144 offset:51200
	ds_read_b128 v[188:191], v144 offset:52224
	ds_read_b128 v[192:195], v144 offset:53248
	ds_read_b128 v[196:199], v144 offset:54272
	ds_read_b128 v[200:203], v144 offset:55296
	ds_read_b128 v[204:207], v144 offset:56320
	s_add_u32 s64, s62, 0x80
	s_addc_u32 s65, s63, 0
	s_mov_b32 m0, s67
	s_nop 0
	global_load_lds_dwordx4 v140, s[64:65]
	s_nop 1
	s_add_u32 s62, s62, 0x80080
	s_mov_b32 m0, s68
	s_nop 0
	global_load_lds_dwordx4 v142, s[64:65]
	s_nop 1
	s_addc_u32 s63, s63, 0
	s_mov_b32 m0, s71
	s_nop 0
	global_load_lds_dwordx4 v140, s[62:63]
	s_nop 1
	s_nop 0
	s_mov_b32 m0, s72
	s_nop 0
	global_load_lds_dwordx4 v142, s[62:63]
	s_nop 1
	s_nop 0
	s_waitcnt vmcnt(6)
	s_waitcnt lgkmcnt(0)
	s_setprio 1
	s_barrier
	v_mfma_f32_16x16x32_bf16 v[62:65], v[136:139], v[176:179], v[62:65]
	v_mfma_f32_16x16x32_bf16 v[78:81], v[152:155], v[176:179], v[78:81]
	v_mfma_f32_16x16x32_bf16 v[70:73], v[136:139], v[184:187], v[70:73]
	v_mfma_f32_16x16x32_bf16 v[90:93], v[152:155], v[184:187], v[90:93]
	v_mfma_f32_16x16x32_bf16 v[82:85], v[136:139], v[192:195], v[82:85]
	v_mfma_f32_16x16x32_bf16 v[106:109], v[152:155], v[192:195], v[106:109]
	v_mfma_f32_16x16x32_bf16 v[98:101], v[136:139], v[200:203], v[98:101]
	v_mfma_f32_16x16x32_bf16 v[118:121], v[152:155], v[200:203], v[118:121]
	v_mfma_f32_16x16x32_bf16 v[74:77], v[160:163], v[176:179], v[74:77]
	v_mfma_f32_16x16x32_bf16 v[94:97], v[168:171], v[176:179], v[94:97]
	v_mfma_f32_16x16x32_bf16 v[86:89], v[160:163], v[184:187], v[86:89]
	v_mfma_f32_16x16x32_bf16 v[110:113], v[168:171], v[184:187], v[110:113]
	v_mfma_f32_16x16x32_bf16 v[102:105], v[160:163], v[192:195], v[102:105]
	v_mfma_f32_16x16x32_bf16 v[122:125], v[168:171], v[192:195], v[122:125]
	v_mfma_f32_16x16x32_bf16 v[114:117], v[160:163], v[200:203], v[114:117]
	v_mfma_f32_16x16x32_bf16 v[126:129], v[168:171], v[200:203], v[126:129]
	v_mfma_f32_16x16x32_bf16 v[62:65], v[148:151], v[180:183], v[62:65]
	v_mfma_f32_16x16x32_bf16 v[78:81], v[156:159], v[180:183], v[78:81]
	v_mfma_f32_16x16x32_bf16 v[70:73], v[148:151], v[188:191], v[70:73]
	v_mfma_f32_16x16x32_bf16 v[90:93], v[156:159], v[188:191], v[90:93]
	v_mfma_f32_16x16x32_bf16 v[82:85], v[148:151], v[196:199], v[82:85]
	v_mfma_f32_16x16x32_bf16 v[106:109], v[156:159], v[196:199], v[106:109]
	v_mfma_f32_16x16x32_bf16 v[98:101], v[148:151], v[204:207], v[98:101]
	v_mfma_f32_16x16x32_bf16 v[118:121], v[156:159], v[204:207], v[118:121]
	v_mfma_f32_16x16x32_bf16 v[74:77], v[164:167], v[180:183], v[74:77]
	v_mfma_f32_16x16x32_bf16 v[94:97], v[172:175], v[180:183], v[94:97]
	v_mfma_f32_16x16x32_bf16 v[86:89], v[164:167], v[188:191], v[86:89]
	v_mfma_f32_16x16x32_bf16 v[110:113], v[172:175], v[188:191], v[110:113]
	v_mfma_f32_16x16x32_bf16 v[102:105], v[164:167], v[196:199], v[102:105]
	v_mfma_f32_16x16x32_bf16 v[122:125], v[172:175], v[196:199], v[122:125]
	v_mfma_f32_16x16x32_bf16 v[114:117], v[164:167], v[204:207], v[114:117]
	v_mfma_f32_16x16x32_bf16 v[126:129], v[172:175], v[204:207], v[126:129]
	s_barrier
	s_setprio 0
	s_add_i32 s83, s83, 2
	s_add_u32 s47, s47, 0x100
	s_addc_u32 s80, s80, 0
	s_add_u32 s81, s81, 0x100
	s_addc_u32 s82, s82, 0
	s_add_u32 s4, s4, 0x100
	s_addc_u32 s5, s5, 0
	s_cmp_gt_u32 s83, 29
	s_cbranch_scc1 .LBB0_869

; #define PG8_STAGE(bufoff, gbase, voff) do { _Pragma("unroll") for (int _i = 0; _i < 2; ++_i) { \
;         const unsigned m0v_ = (unsigned)(uintptr_t)(lds + (bufoff) + ldsw + _i * 8192); \
;         asm volatile("s_mov_b32 m0, %0\n\ts_nop 0\n\tglobal_load_lds_dwordx4 %1, %2\n\ts_nop 1" :: "s"(m0v_), "v"((voff)[_i]), "s"((const char*)(gbase)) : "m0", "memory"); } } while (0)
; #define PG8_LDA(dst, b, h) do { _Pragma("unroll") for (int m = 0; m < 4; ++m) _Pragma("unroll") for (int k = 0; k < 2; ++k) dst[m][k] = *(const LAS bf16x8*)(lds + PG8_SA(b, h) + aoff + m * 2048 + k * 1024); } while (0)
; #define PG8_LDB(dst, b, h) do { _Pragma("unroll") for (int n = 0; n < 2; ++n) _Pragma("unroll") for (int k = 0; k < 2; ++k) dst[n][k] = *(const LAS bf16x8*)(lds + PG8_SB(b, h) + boff + n * 2048 + k * 1024); } while (0)
; #define PG8_MMA(ai, bj, At, Bt) do { _Pragma("unroll") for (int m = 0; m < 4; ++m) _Pragma("unroll") for (int n = 0; n < 2; ++n) _Pragma("unroll") for (int k = 0; k < 2; ++k) \
;         acc[ai][bj][m][n] = __builtin_amdgcn_mfma_f32_16x16x32_bf16(Bt[n][k], At[m][k], acc[ai][bj][m][n], 0, 0, 0); } while (0)
; #define PG8_WAIT_V(n) asm volatile("s_waitcnt vmcnt(" #n ")" ::: "memory")
; #define PG8_WAIT_L(n) asm volatile("s_waitcnt lgkmcnt(" #n ")" ::: "memory")
; template <class Prob, class Epi, class Sched>
; __device__ __forceinline__ void gemm_phase(LAS unsigned char* lds, const Prob& P, const Sched& S, const Epi& E) {
;     ...
;             const char* a1 = cA + (size_t)(t + 1) * kstep;
;             const char* a2 = last ? nA : cA + (size_t)(t + 2) * kstep; const char* b2 = last ? nB : cB + (size_t)(t + 2) * kstep;
;             const char* a3 = a2 + kstep; const char* b3 = b2 + kstep;
;             PG8_LDB(B0, 0, 0); PG8_LDB(B1, 0, 1); PG8_SCHED; PG8_LDA(At, 0, 0); PG8_STAGE(PG8_SA(1, 1), a1 + hstepA, voffA);
;             PG8_WAIT_V(8); PG8_WAIT_L(0); PG8_BAR; __builtin_amdgcn_s_setprio(1); PG8_MMA(0, 0, At, B0); PG8_MMA(0, 1, At, B1); __builtin_amdgcn_s_setprio(0); PG8_BAR; PG8_SCHED;
;             PG8_LDA(At, 0, 1); PG8_STAGE(PG8_SB(0, 0), b2, voffB); PG8_STAGE(PG8_SB(0, 1), b2 + hstepB, voffB); PG8_STAGE(PG8_SA(0, 0), a2, voffA);
;             PG8_WAIT_V(8); PG8_WAIT_L(0); PG8_BAR; __builtin_amdgcn_s_setprio(1); PG8_MMA(1, 0, At, B0); PG8_MMA(1, 1, At, B1); __builtin_amdgcn_s_setprio(0); PG8_BAR; PG8_SCHED;
.LBB0_963:
	ds_read_b128 v[26:29], v199
	ds_read_b128 v[62:65], v199 offset:1024
	ds_read_b128 v[138:141], v199 offset:2048
	ds_read_b128 v[142:145], v199 offset:3072
	ds_read_b128 v[146:149], v200
	ds_read_b128 v[150:153], v200 offset:1024
	ds_read_b128 v[154:157], v200 offset:2048
	ds_read_b128 v[158:161], v200 offset:3072
	s_cmp_eq_u32 s65, 28
	s_cselect_b32 s54, s58, s49
	s_cselect_b32 s55, s59, s51
	s_cselect_b32 s8, s60, s63
	s_cselect_b32 s9, s61, s64
	s_add_u32 s6, s54, 0x80
	s_addc_u32 s7, s55, 0
	ds_read_b128 v[162:165], v201
	ds_read_b128 v[166:169], v201 offset:1024
	ds_read_b128 v[170:173], v201 offset:2048
	ds_read_b128 v[174:177], v201 offset:3072
	ds_read_b128 v[178:181], v201 offset:4096
	ds_read_b128 v[182:185], v201 offset:5120
	ds_read_b128 v[206:209], v201 offset:6144
	ds_read_b128 v[210:213], v201 offset:7168
	s_sub_u32 s98, s4, 0x80000
	s_subb_u32 s99, s5, 0
	s_mov_b32 m0, s76
	s_nop 0
	global_load_lds_dwordx4 v1, s[98:99]
	s_nop 1
	s_nop 0
	s_mov_b32 m0, s77
	s_nop 0
	global_load_lds_dwordx4 v197, s[98:99]
	s_nop 1
	s_mov_b32 m0, s81
	s_nop 0
	global_load_lds_dwordx4 v1, s[4:5]
	s_nop 1
	s_nop 0
	s_mov_b32 m0, s88
	s_nop 0
	global_load_lds_dwordx4 v197, s[4:5]
	s_nop 1
	s_waitcnt vmcnt(8)
	s_waitcnt lgkmcnt(0)
	s_setprio 1
	s_barrier
	v_mfma_f32_16x16x32_bf16 v[134:137], v[26:29], v[162:165], v[134:137]
	v_mfma_f32_16x16x32_bf16 v[70:73], v[138:141], v[162:165], v[70:73]
	v_mfma_f32_16x16x32_bf16 v[102:105], v[26:29], v[170:173], v[102:105]
	v_mfma_f32_16x16x32_bf16 v[82:85], v[138:141], v[170:173], v[82:85]
	v_mfma_f32_16x16x32_bf16 v[78:81], v[26:29], v[178:181], v[78:81]
	v_mfma_f32_16x16x32_bf16 v[14:17], v[138:141], v[178:181], v[14:17]
	v_mfma_f32_16x16x32_bf16 v[130:133], v[26:29], v[206:209], v[130:133]
	v_mfma_f32_16x16x32_bf16 v[126:129], v[138:141], v[206:209], v[126:129]
	v_mfma_f32_16x16x32_bf16 v[66:69], v[146:149], v[162:165], v[66:69]
	v_mfma_f32_16x16x32_bf16 v[54:57], v[154:157], v[162:165], v[54:57]
	v_mfma_f32_16x16x32_bf16 v[98:101], v[146:149], v[170:173], v[98:101]
	v_mfma_f32_16x16x32_bf16 v[86:89], v[154:157], v[170:173], v[86:89]
	v_mfma_f32_16x16x32_bf16 v[74:77], v[146:149], v[178:181], v[74:77]
	v_mfma_f32_16x16x32_bf16 v[10:13], v[154:157], v[178:181], v[10:13]
	v_mfma_f32_16x16x32_bf16 v[122:125], v[146:149], v[206:209], v[122:125]
	v_mfma_f32_16x16x32_bf16 v[58:61], v[154:157], v[206:209], v[58:61]
	v_mfma_f32_16x16x32_bf16 v[134:137], v[62:65], v[166:169], v[134:137]
	v_mfma_f32_16x16x32_bf16 v[70:73], v[142:145], v[166:169], v[70:73]
	v_mfma_f32_16x16x32_bf16 v[102:105], v[62:65], v[174:177], v[102:105]
	v_mfma_f32_16x16x32_bf16 v[82:85], v[142:145], v[174:177], v[82:85]
	v_mfma_f32_16x16x32_bf16 v[78:81], v[62:65], v[182:185], v[78:81]
	v_mfma_f32_16x16x32_bf16 v[14:17], v[142:145], v[182:185], v[14:17]
	v_mfma_f32_16x16x32_bf16 v[130:133], v[62:65], v[210:213], v[130:133]
	v_mfma_f32_16x16x32_bf16 v[126:129], v[142:145], v[210:213], v[126:129]
	v_mfma_f32_16x16x32_bf16 v[66:69], v[150:153], v[166:169], v[66:69]
	v_mfma_f32_16x16x32_bf16 v[54:57], v[158:161], v[166:169], v[54:57]
	v_mfma_f32_16x16x32_bf16 v[98:101], v[150:153], v[174:177], v[98:101]
	v_mfma_f32_16x16x32_bf16 v[86:89], v[158:161], v[174:177], v[86:89]
	v_mfma_f32_16x16x32_bf16 v[74:77], v[150:153], v[182:185], v[74:77]
	v_mfma_f32_16x16x32_bf16 v[10:13], v[158:161], v[182:185], v[10:13]
	v_mfma_f32_16x16x32_bf16 v[122:125], v[150:153], v[210:213], v[122:125]
	v_mfma_f32_16x16x32_bf16 v[58:61], v[158:161], v[210:213], v[58:61]
	s_barrier
	s_setprio 0
	ds_read_b128 v[162:165], v201 offset:16384
	ds_read_b128 v[166:169], v201 offset:17408
	ds_read_b128 v[170:173], v201 offset:18432
	ds_read_b128 v[174:177], v201 offset:19456
	ds_read_b128 v[178:181], v201 offset:20480
	ds_read_b128 v[182:185], v201 offset:21504
	ds_read_b128 v[206:209], v201 offset:22528
	ds_read_b128 v[210:213], v201 offset:23552
	s_mov_b32 m0, s53
	s_nop 0
	global_load_lds_dwordx4 v196, s[8:9]
	s_nop 1
	s_add_u32 s90, s8, 0x80000
	s_mov_b32 m0, s56
	s_nop 0
	global_load_lds_dwordx4 v198, s[8:9]
	s_nop 1
	s_addc_u32 s91, s9, 0
	s_mov_b32 m0, s57
	s_nop 0
	global_load_lds_dwordx4 v196, s[90:91]
	s_nop 1
	s_nop 0
	s_mov_b32 m0, s66
	s_nop 0
	global_load_lds_dwordx4 v198, s[90:91]
	s_nop 1
	s_nop 0
	s_waitcnt vmcnt(6)
	s_waitcnt lgkmcnt(0)
	s_setprio 1
	s_barrier
	v_mfma_f32_16x16x32_bf16 v[118:121], v[26:29], v[162:165], v[118:121]
	v_mfma_f32_16x16x32_bf16 v[30:33], v[138:141], v[162:165], v[30:33]
	v_mfma_f32_16x16x32_bf16 v[42:45], v[26:29], v[170:173], v[42:45]
	v_mfma_f32_16x16x32_bf16 v[6:9], v[138:141], v[170:173], v[6:9]
	v_mfma_f32_16x16x32_bf16 v[94:97], v[26:29], v[178:181], v[94:97]
	v_mfma_f32_16x16x32_bf16 v[46:49], v[138:141], v[178:181], v[46:49]
	v_mfma_f32_16x16x32_bf16 v[26:29], v[26:29], v[206:209], v[114:117]
	v_mfma_f32_16x16x32_bf16 v[34:37], v[146:149], v[162:165], v[34:37]
	v_mfma_f32_16x16x32_bf16 v[18:21], v[154:157], v[162:165], v[18:21]
	v_mfma_f32_16x16x32_bf16 v[38:41], v[146:149], v[170:173], v[38:41]
	v_mfma_f32_16x16x32_bf16 v[2:5], v[154:157], v[170:173], v[2:5]
	v_mfma_f32_16x16x32_bf16 v[90:93], v[146:149], v[178:181], v[90:93]
	v_mfma_f32_16x16x32_bf16 v[50:53], v[154:157], v[178:181], v[50:53]
	v_mfma_f32_16x16x32_bf16 v[106:109], v[146:149], v[206:209], v[106:109]
	v_mfma_f32_16x16x32_bf16 v[22:25], v[154:157], v[206:209], v[22:25]
	v_mfma_f32_16x16x32_bf16 v[118:121], v[62:65], v[166:169], v[118:121]
	v_mfma_f32_16x16x32_bf16 v[30:33], v[142:145], v[166:169], v[30:33]
	v_mfma_f32_16x16x32_bf16 v[42:45], v[62:65], v[174:177], v[42:45]
	v_mfma_f32_16x16x32_bf16 v[6:9], v[142:145], v[174:177], v[6:9]
	v_mfma_f32_16x16x32_bf16 v[94:97], v[62:65], v[182:185], v[94:97]
	v_mfma_f32_16x16x32_bf16 v[46:49], v[142:145], v[182:185], v[46:49]
	v_mfma_f32_16x16x32_bf16 v[26:29], v[62:65], v[210:213], v[26:29]
	v_mfma_f32_16x16x32_bf16 v[62:65], v[138:141], v[206:209], v[110:113]
	v_mfma_f32_16x16x32_bf16 v[34:37], v[150:153], v[166:169], v[34:37]
	v_mfma_f32_16x16x32_bf16 v[18:21], v[158:161], v[166:169], v[18:21]
	v_mfma_f32_16x16x32_bf16 v[38:41], v[150:153], v[174:177], v[38:41]
	v_mfma_f32_16x16x32_bf16 v[2:5], v[158:161], v[174:177], v[2:5]
	v_mfma_f32_16x16x32_bf16 v[90:93], v[150:153], v[182:185], v[90:93]
	v_mfma_f32_16x16x32_bf16 v[50:53], v[158:161], v[182:185], v[50:53]
	v_mfma_f32_16x16x32_bf16 v[106:109], v[150:153], v[210:213], v[106:109]
	v_mfma_f32_16x16x32_bf16 v[22:25], v[158:161], v[210:213], v[22:25]
	v_mfma_f32_16x16x32_bf16 v[62:65], v[142:145], v[210:213], v[62:65]
	s_barrier
; #define PG8_STAGE(bufoff, gbase, voff) do { _Pragma("unroll") for (int _i = 0; _i < 2; ++_i) { \
;         const unsigned m0v_ = (unsigned)(uintptr_t)(lds + (bufoff) + ldsw + _i * 8192); \
;         asm volatile("s_mov_b32 m0, %0\n\ts_nop 0\n\tglobal_load_lds_dwordx4 %1, %2\n\ts_nop 1" :: "s"(m0v_), "v"((voff)[_i]), "s"((const char*)(gbase)) : "m0", "memory"); } } while (0)
; #define PG8_LDA(dst, b, h) do { _Pragma("unroll") for (int m = 0; m < 4; ++m) _Pragma("unroll") for (int k = 0; k < 2; ++k) dst[m][k] = *(const LAS bf16x8*)(lds + PG8_SA(b, h) + aoff + m * 2048 + k * 1024); } while (0)
; #define PG8_LDB(dst, b, h) do { _Pragma("unroll") for (int n = 0; n < 2; ++n) _Pragma("unroll") for (int k = 0; k < 2; ++k) dst[n][k] = *(const LAS bf16x8*)(lds + PG8_SB(b, h) + boff + n * 2048 + k * 1024); } while (0)
; #define PG8_MMA(ai, bj, At, Bt) do { _Pragma("unroll") for (int m = 0; m < 4; ++m) _Pragma("unroll") for (int n = 0; n < 2; ++n) _Pragma("unroll") for (int k = 0; k < 2; ++k) \
;         acc[ai][bj][m][n] = __builtin_amdgcn_mfma_f32_16x16x32_bf16(Bt[n][k], At[m][k], acc[ai][bj][m][n], 0, 0, 0); } while (0)
; #define PG8_WAIT_V(n) asm volatile("s_waitcnt vmcnt(" #n ")" ::: "memory")
; #define PG8_WAIT_L(n) asm volatile("s_waitcnt lgkmcnt(" #n ")" ::: "memory")
; #define PG8_BAR __builtin_amdgcn_s_barrier()
; #define PG8_SCHED __builtin_amdgcn_sched_barrier(0)
; template <class Prob, class Epi, class Sched>
; __device__ __forceinline__ void gemm_phase(LAS unsigned char* lds, const Prob& P, const Sched& S, const Epi& E) {
;     ...
;             PG8_LDB(B0, 1, 0); PG8_LDB(B1, 1, 1); PG8_SCHED; PG8_LDA(At, 1, 0); PG8_STAGE(PG8_SA(0, 1), a2 + hstepA, voffA);
;             PG8_WAIT_V(8); PG8_WAIT_L(0); PG8_BAR; __builtin_amdgcn_s_setprio(1); PG8_MMA(0, 0, At, B0); PG8_MMA(0, 1, At, B1); __builtin_amdgcn_s_setprio(0); PG8_BAR; PG8_SCHED;
;             PG8_LDA(At, 1, 1); PG8_STAGE(PG8_SB(1, 0), b3, voffB); PG8_STAGE(PG8_SB(1, 1), b3 + hstepB, voffB); PG8_STAGE(PG8_SA(1, 0), a3, voffA);
;             PG8_WAIT_V(8); PG8_WAIT_L(0); PG8_BAR; __builtin_amdgcn_s_setprio(1); PG8_MMA(1, 0, At, B0); PG8_MMA(1, 1, At, B1); __builtin_amdgcn_s_setprio(0); PG8_BAR; PG8_SCHED;
;         }
	s_setprio 0
	ds_read_b128 v[110:113], v202
	ds_read_b128 v[114:117], v202 offset:1024
	ds_read_b128 v[138:141], v202 offset:2048
	ds_read_b128 v[142:145], v202 offset:3072
	ds_read_b128 v[146:149], v203
	ds_read_b128 v[150:153], v203 offset:1024
	ds_read_b128 v[154:157], v203 offset:2048
	ds_read_b128 v[158:161], v203 offset:3072
	ds_read_b128 v[162:165], v201 offset:32768
	ds_read_b128 v[166:169], v201 offset:33792
	ds_read_b128 v[170:173], v201 offset:34816
	ds_read_b128 v[174:177], v201 offset:35840
	ds_read_b128 v[178:181], v201 offset:36864
	ds_read_b128 v[182:185], v201 offset:37888
	ds_read_b128 v[206:209], v201 offset:38912
	ds_read_b128 v[210:213], v201 offset:39936
	s_mov_b32 m0, s35
	s_nop 0
	global_load_lds_dwordx4 v1, s[54:55]
	s_nop 1
	s_nop 0
	s_mov_b32 m0, s67
	s_nop 0
	global_load_lds_dwordx4 v197, s[54:55]
	s_nop 1
	s_add_u32 s54, s54, 0x80000
	s_addc_u32 s55, s55, 0
	s_mov_b32 m0, s68
	s_nop 0
	global_load_lds_dwordx4 v1, s[54:55]
	s_nop 1
	s_nop 0
	s_mov_b32 m0, s69
	s_nop 0
	global_load_lds_dwordx4 v197, s[54:55]
	s_nop 1
	s_waitcnt vmcnt(8)
	s_waitcnt lgkmcnt(0)
	s_setprio 1
	s_barrier
	v_mfma_f32_16x16x32_bf16 v[134:137], v[110:113], v[162:165], v[134:137]
	v_mfma_f32_16x16x32_bf16 v[70:73], v[138:141], v[162:165], v[70:73]
	v_mfma_f32_16x16x32_bf16 v[102:105], v[110:113], v[170:173], v[102:105]
	v_mfma_f32_16x16x32_bf16 v[82:85], v[138:141], v[170:173], v[82:85]
	v_mfma_f32_16x16x32_bf16 v[78:81], v[110:113], v[178:181], v[78:81]
	v_mfma_f32_16x16x32_bf16 v[14:17], v[138:141], v[178:181], v[14:17]
	v_mfma_f32_16x16x32_bf16 v[130:133], v[110:113], v[206:209], v[130:133]
	v_mfma_f32_16x16x32_bf16 v[126:129], v[138:141], v[206:209], v[126:129]
	v_mfma_f32_16x16x32_bf16 v[66:69], v[146:149], v[162:165], v[66:69]
	v_mfma_f32_16x16x32_bf16 v[54:57], v[154:157], v[162:165], v[54:57]
	v_mfma_f32_16x16x32_bf16 v[98:101], v[146:149], v[170:173], v[98:101]
	v_mfma_f32_16x16x32_bf16 v[86:89], v[154:157], v[170:173], v[86:89]
	v_mfma_f32_16x16x32_bf16 v[74:77], v[146:149], v[178:181], v[74:77]
	v_mfma_f32_16x16x32_bf16 v[10:13], v[154:157], v[178:181], v[10:13]
	v_mfma_f32_16x16x32_bf16 v[122:125], v[146:149], v[206:209], v[122:125]
	v_mfma_f32_16x16x32_bf16 v[58:61], v[154:157], v[206:209], v[58:61]
	v_mfma_f32_16x16x32_bf16 v[134:137], v[114:117], v[166:169], v[134:137]
	v_mfma_f32_16x16x32_bf16 v[70:73], v[142:145], v[166:169], v[70:73]
	v_mfma_f32_16x16x32_bf16 v[102:105], v[114:117], v[174:177], v[102:105]
	v_mfma_f32_16x16x32_bf16 v[82:85], v[142:145], v[174:177], v[82:85]
	v_mfma_f32_16x16x32_bf16 v[78:81], v[114:117], v[182:185], v[78:81]
	v_mfma_f32_16x16x32_bf16 v[14:17], v[142:145], v[182:185], v[14:17]
	v_mfma_f32_16x16x32_bf16 v[130:133], v[114:117], v[210:213], v[130:133]
	v_mfma_f32_16x16x32_bf16 v[126:129], v[142:145], v[210:213], v[126:129]
	v_mfma_f32_16x16x32_bf16 v[66:69], v[150:153], v[166:169], v[66:69]
	v_mfma_f32_16x16x32_bf16 v[54:57], v[158:161], v[166:169], v[54:57]
	v_mfma_f32_16x16x32_bf16 v[98:101], v[150:153], v[174:177], v[98:101]
	v_mfma_f32_16x16x32_bf16 v[86:89], v[158:161], v[174:177], v[86:89]
	v_mfma_f32_16x16x32_bf16 v[74:77], v[150:153], v[182:185], v[74:77]
	v_mfma_f32_16x16x32_bf16 v[10:13], v[158:161], v[182:185], v[10:13]
	v_mfma_f32_16x16x32_bf16 v[122:125], v[150:153], v[210:213], v[122:125]
	v_mfma_f32_16x16x32_bf16 v[58:61], v[158:161], v[210:213], v[58:61]
	s_barrier
	s_setprio 0
	ds_read_b128 v[162:165], v201 offset:49152
	ds_read_b128 v[166:169], v201 offset:50176
	ds_read_b128 v[170:173], v201 offset:51200
	ds_read_b128 v[174:177], v201 offset:52224
	ds_read_b128 v[178:181], v201 offset:53248
	ds_read_b128 v[182:185], v201 offset:54272
	ds_read_b128 v[206:209], v201 offset:55296
	ds_read_b128 v[210:213], v201 offset:56320
	s_add_u32 s54, s8, 0x80
	s_addc_u32 s55, s9, 0
	s_mov_b32 m0, s74
	s_nop 0
	global_load_lds_dwordx4 v196, s[54:55]
	s_nop 1
	s_add_u32 s8, s8, 0x80080
	s_mov_b32 m0, s75
	s_nop 0
	global_load_lds_dwordx4 v198, s[54:55]
	s_nop 1
	s_addc_u32 s9, s9, 0
	s_mov_b32 m0, s78
	s_nop 0
	global_load_lds_dwordx4 v196, s[8:9]
	s_nop 1
	s_nop 0
	s_mov_b32 m0, s79
	s_nop 0
	global_load_lds_dwordx4 v198, s[8:9]
	s_nop 1
	s_nop 0
	s_waitcnt vmcnt(6)
	s_waitcnt lgkmcnt(0)
	s_setprio 1
	s_barrier
	v_mfma_f32_16x16x32_bf16 v[118:121], v[110:113], v[162:165], v[118:121]
	v_mfma_f32_16x16x32_bf16 v[42:45], v[110:113], v[170:173], v[42:45]
	v_mfma_f32_16x16x32_bf16 v[94:97], v[110:113], v[178:181], v[94:97]
	v_mfma_f32_16x16x32_bf16 v[26:29], v[110:113], v[206:209], v[26:29]
	v_mfma_f32_16x16x32_bf16 v[118:121], v[114:117], v[166:169], v[118:121]
	v_mfma_f32_16x16x32_bf16 v[42:45], v[114:117], v[174:177], v[42:45]
	v_mfma_f32_16x16x32_bf16 v[94:97], v[114:117], v[182:185], v[94:97]
	v_mfma_f32_16x16x32_bf16 v[114:117], v[114:117], v[210:213], v[26:29]
	v_mfma_f32_16x16x32_bf16 v[26:29], v[138:141], v[206:209], v[62:65]
	v_mfma_f32_16x16x32_bf16 v[110:113], v[142:145], v[210:213], v[26:29]
	v_mfma_f32_16x16x32_bf16 v[26:29], v[146:149], v[162:165], v[34:37]
	v_mfma_f32_16x16x32_bf16 v[34:37], v[150:153], v[166:169], v[26:29]
	v_mfma_f32_16x16x32_bf16 v[26:29], v[146:149], v[170:173], v[38:41]
	v_mfma_f32_16x16x32_bf16 v[38:41], v[150:153], v[174:177], v[26:29]
	v_mfma_f32_16x16x32_bf16 v[26:29], v[146:149], v[178:181], v[90:93]
	v_mfma_f32_16x16x32_bf16 v[90:93], v[150:153], v[182:185], v[26:29]
	v_mfma_f32_16x16x32_bf16 v[26:29], v[154:157], v[178:181], v[50:53]
	v_mfma_f32_16x16x32_bf16 v[30:33], v[138:141], v[162:165], v[30:33]
	v_mfma_f32_16x16x32_bf16 v[6:9], v[138:141], v[170:173], v[6:9]
	v_mfma_f32_16x16x32_bf16 v[46:49], v[138:141], v[178:181], v[46:49]
	v_mfma_f32_16x16x32_bf16 v[18:21], v[154:157], v[162:165], v[18:21]
	v_mfma_f32_16x16x32_bf16 v[2:5], v[154:157], v[170:173], v[2:5]
	v_mfma_f32_16x16x32_bf16 v[50:53], v[158:161], v[182:185], v[26:29]
	v_mfma_f32_16x16x32_bf16 v[26:29], v[146:149], v[206:209], v[106:109]
	v_mfma_f32_16x16x32_bf16 v[22:25], v[154:157], v[206:209], v[22:25]
	v_mfma_f32_16x16x32_bf16 v[30:33], v[142:145], v[166:169], v[30:33]
	v_mfma_f32_16x16x32_bf16 v[6:9], v[142:145], v[174:177], v[6:9]
	v_mfma_f32_16x16x32_bf16 v[46:49], v[142:145], v[182:185], v[46:49]
	v_mfma_f32_16x16x32_bf16 v[18:21], v[158:161], v[166:169], v[18:21]
	v_mfma_f32_16x16x32_bf16 v[2:5], v[158:161], v[174:177], v[2:5]
	v_mfma_f32_16x16x32_bf16 v[106:109], v[150:153], v[210:213], v[26:29]
	v_mfma_f32_16x16x32_bf16 v[22:25], v[158:161], v[210:213], v[22:25]
	s_barrier
	s_setprio 0
	s_add_i32 s65, s65, 2
	s_add_u32 s49, s49, 0x100
	s_addc_u32 s51, s51, 0
	s_add_u32 s63, s63, 0x100
	s_addc_u32 s64, s64, 0
	s_add_u32 s4, s4, 0x100
	s_addc_u32 s5, s5, 0
	s_cmp_gt_u32 s65, 29
	s_cbranch_scc0 .LBB0_963
	s_and_b64 vcc, exec, s[36:37]
	s_cbranch_vccz .LBB0_966
	s_barrier

; #define PG8_STAGE(bufoff, gbase, voff) do { _Pragma("unroll") for (int _i = 0; _i < 2; ++_i) { \
;         const unsigned m0v_ = (unsigned)(uintptr_t)(lds + (bufoff) + ldsw + _i * 8192); \
;         asm volatile("s_mov_b32 m0, %0\n\ts_nop 0\n\tglobal_load_lds_dwordx4 %1, %2\n\ts_nop 1" :: "s"(m0v_), "v"((voff)[_i]), "s"((const char*)(gbase)) : "m0", "memory"); } } while (0)
; #define PG8_LDA(dst, b, h) do { _Pragma("unroll") for (int m = 0; m < 4; ++m) _Pragma("unroll") for (int k = 0; k < 2; ++k) dst[m][k] = *(const LAS bf16x8*)(lds + PG8_SA(b, h) + aoff + m * 2048 + k * 1024); } while (0)
; #define PG8_LDB(dst, b, h) do { _Pragma("unroll") for (int n = 0; n < 2; ++n) _Pragma("unroll") for (int k = 0; k < 2; ++k) dst[n][k] = *(const LAS bf16x8*)(lds + PG8_SB(b, h) + boff + n * 2048 + k * 1024); } while (0)
; #define PG8_MMA(ai, bj, At, Bt) do { _Pragma("unroll") for (int m = 0; m < 4; ++m) _Pragma("unroll") for (int n = 0; n < 2; ++n) _Pragma("unroll") for (int k = 0; k < 2; ++k) \
;         acc[ai][bj][m][n] = __builtin_amdgcn_mfma_f32_16x16x32_bf16(Bt[n][k], At[m][k], acc[ai][bj][m][n], 0, 0, 0); } while (0)
; #define PG8_WAIT_V(n) asm volatile("s_waitcnt vmcnt(" #n ")" ::: "memory")
; #define PG8_WAIT_L(n) asm volatile("s_waitcnt lgkmcnt(" #n ")" ::: "memory")
; template <class Prob, class Epi, class Sched>
; __device__ __forceinline__ void gemm_phase(LAS unsigned char* lds, const Prob& P, const Sched& S, const Epi& E) {
;     ...
;             const char* a1 = cA + (size_t)(t + 1) * kstep;
;             const char* a2 = last ? nA : cA + (size_t)(t + 2) * kstep; const char* b2 = last ? nB : cB + (size_t)(t + 2) * kstep;
;             const char* a3 = a2 + kstep; const char* b3 = b2 + kstep;
;             PG8_LDB(B0, 0, 0); PG8_LDB(B1, 0, 1); PG8_SCHED; PG8_LDA(At, 0, 0); PG8_STAGE(PG8_SA(1, 1), a1 + hstepA, voffA);
;             PG8_WAIT_V(8); PG8_WAIT_L(0); PG8_BAR; __builtin_amdgcn_s_setprio(1); PG8_MMA(0, 0, At, B0); PG8_MMA(0, 1, At, B1); __builtin_amdgcn_s_setprio(0); PG8_BAR; PG8_SCHED;
;             PG8_LDA(At, 0, 1); PG8_STAGE(PG8_SB(0, 0), b2, voffB); PG8_STAGE(PG8_SB(0, 1), b2 + hstepB, voffB); PG8_STAGE(PG8_SA(0, 0), a2, voffA);
;             PG8_WAIT_V(8); PG8_WAIT_L(0); PG8_BAR; __builtin_amdgcn_s_setprio(1); PG8_MMA(1, 0, At, B0); PG8_MMA(1, 1, At, B1); __builtin_amdgcn_s_setprio(0); PG8_BAR; PG8_SCHED;
.LBB0_1159:
	v_add_u32_e32 v142, 0x10000, v168
	v_add_u32_e32 v146, 0x14000, v168
	s_add_u32 s6, s2, s4
	ds_read_b128 v[130:133], v142
	ds_read_b128 v[134:137], v142 offset:1024
	ds_read_b128 v[138:141], v142 offset:2048
	ds_read_b128 v[142:145], v142 offset:3072
	ds_read_b128 v[148:151], v146
	ds_read_b128 v[164:167], v146 offset:1024
	ds_read_b128 v[174:177], v146 offset:2048
	ds_read_b128 v[178:181], v146 offset:3072
	s_addc_u32 s7, s3, s5
	s_cmpk_eq_i32 s37, 0x54
	s_cselect_b32 s42, s34, s6
	s_cselect_b32 s43, s35, s7
	s_cselect_b32 s39, 0, s4
	s_cselect_b32 s41, 0, s5
	s_add_u32 s6, s42, 0x80
	s_addc_u32 s7, s43, 0
	s_add_u32 s40, s16, s39
	s_addc_u32 s41, s17, s41
	ds_read_b128 v[182:185], v169
	ds_read_b128 v[186:189], v169 offset:1024
	ds_read_b128 v[190:193], v169 offset:2048
	ds_read_b128 v[194:197], v169 offset:3072
	ds_read_b128 v[198:201], v169 offset:4096
	ds_read_b128 v[202:205], v169 offset:5120
	ds_read_b128 v[206:209], v169 offset:6144
	ds_read_b128 v[210:213], v169 offset:7168
	s_add_u32 s39, s10, s4
	s_addc_u32 s45, s31, s5
	s_add_u32 s44, s39, 0xffffff80
	s_addc_u32 s45, s45, -1
	s_sub_u32 s98, s44, 0x160000
	s_subb_u32 s99, s45, 0
	s_mov_b32 m0, s63
	s_nop 0
	global_load_lds_dwordx4 v155, s[98:99]
	s_nop 1
	s_nop 0
	s_mov_b32 m0, s64
	s_nop 0
	global_load_lds_dwordx4 v161, s[98:99]
	s_nop 1
	s_mov_b32 m0, s67
	s_nop 0
	global_load_lds_dwordx4 v155, s[44:45]
	s_nop 1
	s_nop 0
	s_mov_b32 m0, s70
	s_nop 0
	global_load_lds_dwordx4 v161, s[44:45]
	s_nop 1
	s_waitcnt vmcnt(8)
	s_waitcnt lgkmcnt(0)
	s_setprio 1
	s_barrier
	v_mfma_f32_16x16x32_bf16 v[2:5], v[130:133], v[182:185], v[2:5]
	v_mfma_f32_16x16x32_bf16 v[18:21], v[138:141], v[182:185], v[18:21]
	v_mfma_f32_16x16x32_bf16 v[26:29], v[130:133], v[190:193], v[26:29]
	v_mfma_f32_16x16x32_bf16 v[38:41], v[138:141], v[190:193], v[38:41]
	v_mfma_f32_16x16x32_bf16 v[6:9], v[130:133], v[198:201], v[6:9]
	v_mfma_f32_16x16x32_bf16 v[14:17], v[138:141], v[198:201], v[14:17]
	v_mfma_f32_16x16x32_bf16 v[10:13], v[130:133], v[206:209], v[10:13]
	v_mfma_f32_16x16x32_bf16 v[22:25], v[138:141], v[206:209], v[22:25]
	v_mfma_f32_16x16x32_bf16 v[62:65], v[148:151], v[182:185], v[62:65]
	v_mfma_f32_16x16x32_bf16 v[94:97], v[174:177], v[182:185], v[94:97]
	v_mfma_f32_16x16x32_bf16 v[30:33], v[148:151], v[190:193], v[30:33]
	v_mfma_f32_16x16x32_bf16 v[46:49], v[174:177], v[190:193], v[46:49]
	v_mfma_f32_16x16x32_bf16 v[34:37], v[148:151], v[198:201], v[34:37]
	v_mfma_f32_16x16x32_bf16 v[54:57], v[174:177], v[198:201], v[54:57]
	v_mfma_f32_16x16x32_bf16 v[42:45], v[148:151], v[206:209], v[42:45]
	v_mfma_f32_16x16x32_bf16 v[58:61], v[174:177], v[206:209], v[58:61]
	v_mfma_f32_16x16x32_bf16 v[2:5], v[134:137], v[186:189], v[2:5]
	v_mfma_f32_16x16x32_bf16 v[18:21], v[142:145], v[186:189], v[18:21]
	v_mfma_f32_16x16x32_bf16 v[26:29], v[134:137], v[194:197], v[26:29]
	v_mfma_f32_16x16x32_bf16 v[38:41], v[142:145], v[194:197], v[38:41]
	v_mfma_f32_16x16x32_bf16 v[6:9], v[134:137], v[202:205], v[6:9]
	v_mfma_f32_16x16x32_bf16 v[14:17], v[142:145], v[202:205], v[14:17]
	v_mfma_f32_16x16x32_bf16 v[10:13], v[134:137], v[210:213], v[10:13]
	v_mfma_f32_16x16x32_bf16 v[22:25], v[142:145], v[210:213], v[22:25]
	v_mfma_f32_16x16x32_bf16 v[62:65], v[164:167], v[186:189], v[62:65]
	v_mfma_f32_16x16x32_bf16 v[94:97], v[178:181], v[186:189], v[94:97]
	v_mfma_f32_16x16x32_bf16 v[30:33], v[164:167], v[194:197], v[30:33]
	v_mfma_f32_16x16x32_bf16 v[46:49], v[178:181], v[194:197], v[46:49]
	v_mfma_f32_16x16x32_bf16 v[34:37], v[164:167], v[202:205], v[34:37]
	v_mfma_f32_16x16x32_bf16 v[54:57], v[178:181], v[202:205], v[54:57]
	v_mfma_f32_16x16x32_bf16 v[42:45], v[164:167], v[210:213], v[42:45]
	v_mfma_f32_16x16x32_bf16 v[58:61], v[178:181], v[210:213], v[58:61]
	s_barrier
	s_setprio 0
	ds_read_b128 v[182:185], v169 offset:16384
	ds_read_b128 v[186:189], v169 offset:17408
	ds_read_b128 v[190:193], v169 offset:18432
	ds_read_b128 v[194:197], v169 offset:19456
	ds_read_b128 v[198:201], v169 offset:20480
	ds_read_b128 v[202:205], v169 offset:21504
	ds_read_b128 v[206:209], v169 offset:22528
	ds_read_b128 v[210:213], v169 offset:23552
	s_mov_b32 m0, s50
	s_nop 0
	global_load_lds_dwordx4 v159, s[40:41]
	s_nop 1
	s_add_u32 s44, s40, 0x160000
	s_mov_b32 m0, s51
	s_nop 0
	global_load_lds_dwordx4 v163, s[40:41]
	s_nop 1
	s_addc_u32 s45, s41, 0
	s_mov_b32 m0, s52
	s_nop 0
	global_load_lds_dwordx4 v159, s[44:45]
	s_nop 1
	s_nop 0
	s_mov_b32 m0, s53
	s_nop 0
	global_load_lds_dwordx4 v163, s[44:45]
	s_nop 1
	s_nop 0
	s_waitcnt vmcnt(6)
	s_waitcnt lgkmcnt(0)
	s_setprio 1
	s_barrier
; #define PG8_STAGE(bufoff, gbase, voff) do { _Pragma("unroll") for (int _i = 0; _i < 2; ++_i) { \
;         const unsigned m0v_ = (unsigned)(uintptr_t)(lds + (bufoff) + ldsw + _i * 8192); \
;         asm volatile("s_mov_b32 m0, %0\n\ts_nop 0\n\tglobal_load_lds_dwordx4 %1, %2\n\ts_nop 1" :: "s"(m0v_), "v"((voff)[_i]), "s"((const char*)(gbase)) : "m0", "memory"); } } while (0)
; #define PG8_LDA(dst, b, h) do { _Pragma("unroll") for (int m = 0; m < 4; ++m) _Pragma("unroll") for (int k = 0; k < 2; ++k) dst[m][k] = *(const LAS bf16x8*)(lds + PG8_SA(b, h) + aoff + m * 2048 + k * 1024); } while (0)
; #define PG8_LDB(dst, b, h) do { _Pragma("unroll") for (int n = 0; n < 2; ++n) _Pragma("unroll") for (int k = 0; k < 2; ++k) dst[n][k] = *(const LAS bf16x8*)(lds + PG8_SB(b, h) + boff + n * 2048 + k * 1024); } while (0)
; #define PG8_MMA(ai, bj, At, Bt) do { _Pragma("unroll") for (int m = 0; m < 4; ++m) _Pragma("unroll") for (int n = 0; n < 2; ++n) _Pragma("unroll") for (int k = 0; k < 2; ++k) \
;         acc[ai][bj][m][n] = __builtin_amdgcn_mfma_f32_16x16x32_bf16(Bt[n][k], At[m][k], acc[ai][bj][m][n], 0, 0, 0); } while (0)
; #define PG8_WAIT_V(n) asm volatile("s_waitcnt vmcnt(" #n ")" ::: "memory")
; #define PG8_WAIT_L(n) asm volatile("s_waitcnt lgkmcnt(" #n ")" ::: "memory")
; #define PG8_BAR __builtin_amdgcn_s_barrier()
; #define PG8_SCHED __builtin_amdgcn_sched_barrier(0)
; template <class Prob, class Epi, class Sched>
; __device__ __forceinline__ void gemm_phase(LAS unsigned char* lds, const Prob& P, const Sched& S, const Epi& E) {
;     ...
;             PG8_WAIT_V(8); PG8_WAIT_L(0); PG8_BAR; __builtin_amdgcn_s_setprio(1); PG8_MMA(1, 0, At, B0); PG8_MMA(1, 1, At, B1); __builtin_amdgcn_s_setprio(0); PG8_BAR; PG8_SCHED;
;             PG8_LDB(B0, 1, 0); PG8_LDB(B1, 1, 1); PG8_SCHED; PG8_LDA(At, 1, 0); PG8_STAGE(PG8_SA(0, 1), a2 + hstepA, voffA);
;             PG8_WAIT_V(8); PG8_WAIT_L(0); PG8_BAR; __builtin_amdgcn_s_setprio(1); PG8_MMA(0, 0, At, B0); PG8_MMA(0, 1, At, B1); __builtin_amdgcn_s_setprio(0); PG8_BAR; PG8_SCHED;
	v_mfma_f32_16x16x32_bf16 v[78:81], v[130:133], v[182:185], v[78:81]
	v_mfma_f32_16x16x32_bf16 v[90:93], v[138:141], v[182:185], v[90:93]
	v_mfma_f32_16x16x32_bf16 v[74:77], v[130:133], v[190:193], v[74:77]
	v_mfma_f32_16x16x32_bf16 v[86:89], v[138:141], v[190:193], v[86:89]
	v_mfma_f32_16x16x32_bf16 v[70:73], v[130:133], v[198:201], v[70:73]
	v_mfma_f32_16x16x32_bf16 v[82:85], v[138:141], v[198:201], v[82:85]
	v_mfma_f32_16x16x32_bf16 v[66:69], v[130:133], v[206:209], v[66:69]
	v_mfma_f32_16x16x32_bf16 v[50:53], v[138:141], v[206:209], v[50:53]
	v_mfma_f32_16x16x32_bf16 v[114:117], v[148:151], v[182:185], v[114:117]
	v_mfma_f32_16x16x32_bf16 v[126:129], v[174:177], v[182:185], v[126:129]
	v_mfma_f32_16x16x32_bf16 v[110:113], v[148:151], v[190:193], v[110:113]
	v_mfma_f32_16x16x32_bf16 v[122:125], v[174:177], v[190:193], v[122:125]
	v_mfma_f32_16x16x32_bf16 v[106:109], v[148:151], v[198:201], v[106:109]
	v_mfma_f32_16x16x32_bf16 v[118:121], v[174:177], v[198:201], v[118:121]
	v_mfma_f32_16x16x32_bf16 v[102:105], v[148:151], v[206:209], v[102:105]
	v_mfma_f32_16x16x32_bf16 v[98:101], v[174:177], v[206:209], v[98:101]
	v_mfma_f32_16x16x32_bf16 v[78:81], v[134:137], v[186:189], v[78:81]
	v_mfma_f32_16x16x32_bf16 v[90:93], v[142:145], v[186:189], v[90:93]
	v_mfma_f32_16x16x32_bf16 v[74:77], v[134:137], v[194:197], v[74:77]
	v_mfma_f32_16x16x32_bf16 v[86:89], v[142:145], v[194:197], v[86:89]
	v_mfma_f32_16x16x32_bf16 v[70:73], v[134:137], v[202:205], v[70:73]
	v_mfma_f32_16x16x32_bf16 v[82:85], v[142:145], v[202:205], v[82:85]
	v_mfma_f32_16x16x32_bf16 v[66:69], v[134:137], v[210:213], v[66:69]
	v_mfma_f32_16x16x32_bf16 v[50:53], v[142:145], v[210:213], v[50:53]
	v_mfma_f32_16x16x32_bf16 v[114:117], v[164:167], v[186:189], v[114:117]
	v_mfma_f32_16x16x32_bf16 v[126:129], v[178:181], v[186:189], v[126:129]
	v_mfma_f32_16x16x32_bf16 v[110:113], v[164:167], v[194:197], v[110:113]
	v_mfma_f32_16x16x32_bf16 v[122:125], v[178:181], v[194:197], v[122:125]
	v_mfma_f32_16x16x32_bf16 v[106:109], v[164:167], v[202:205], v[106:109]
	v_mfma_f32_16x16x32_bf16 v[118:121], v[178:181], v[202:205], v[118:121]
	v_mfma_f32_16x16x32_bf16 v[102:105], v[164:167], v[210:213], v[102:105]
	v_mfma_f32_16x16x32_bf16 v[98:101], v[178:181], v[210:213], v[98:101]
	s_barrier
	s_setprio 0
	v_add_u32_e32 v142, 0x18000, v168
	v_add_u32_e32 v146, 0x1c000, v168
	ds_read_b128 v[130:133], v142
	ds_read_b128 v[134:137], v142 offset:1024
	ds_read_b128 v[138:141], v142 offset:2048
	ds_read_b128 v[142:145], v142 offset:3072
	ds_read_b128 v[148:151], v146
	ds_read_b128 v[164:167], v146 offset:1024
	ds_read_b128 v[174:177], v146 offset:2048
	ds_read_b128 v[178:181], v146 offset:3072
	ds_read_b128 v[182:185], v169 offset:32768
	ds_read_b128 v[186:189], v169 offset:33792
	ds_read_b128 v[190:193], v169 offset:34816
	ds_read_b128 v[194:197], v169 offset:35840
	ds_read_b128 v[198:201], v169 offset:36864
	ds_read_b128 v[202:205], v169 offset:37888
	ds_read_b128 v[206:209], v169 offset:38912
	ds_read_b128 v[210:213], v169 offset:39936
	s_mov_b32 m0, s9
	s_nop 0
	global_load_lds_dwordx4 v155, s[42:43]
	s_nop 1
	s_nop 0
	s_mov_b32 m0, s54
	s_nop 0
	global_load_lds_dwordx4 v161, s[42:43]
	s_nop 1
	s_add_u32 s42, s42, 0x160000
	s_addc_u32 s43, s43, 0
	s_mov_b32 m0, s55
	s_nop 0
	global_load_lds_dwordx4 v155, s[42:43]
	s_nop 1
	s_nop 0
	s_mov_b32 m0, s56
	s_nop 0
	global_load_lds_dwordx4 v161, s[42:43]
	s_nop 1
	s_waitcnt vmcnt(8)
	s_waitcnt lgkmcnt(0)
	s_setprio 1
	s_barrier
; #define PG8_STAGE(bufoff, gbase, voff) do { _Pragma("unroll") for (int _i = 0; _i < 2; ++_i) { \
;         const unsigned m0v_ = (unsigned)(uintptr_t)(lds + (bufoff) + ldsw + _i * 8192); \
;         asm volatile("s_mov_b32 m0, %0\n\ts_nop 0\n\tglobal_load_lds_dwordx4 %1, %2\n\ts_nop 1" :: "s"(m0v_), "v"((voff)[_i]), "s"((const char*)(gbase)) : "m0", "memory"); } } while (0)
; #define PG8_LDA(dst, b, h) do { _Pragma("unroll") for (int m = 0; m < 4; ++m) _Pragma("unroll") for (int k = 0; k < 2; ++k) dst[m][k] = *(const LAS bf16x8*)(lds + PG8_SA(b, h) + aoff + m * 2048 + k * 1024); } while (0)
; #define PG8_MMA(ai, bj, At, Bt) do { _Pragma("unroll") for (int m = 0; m < 4; ++m) _Pragma("unroll") for (int n = 0; n < 2; ++n) _Pragma("unroll") for (int k = 0; k < 2; ++k) \
;         acc[ai][bj][m][n] = __builtin_amdgcn_mfma_f32_16x16x32_bf16(Bt[n][k], At[m][k], acc[ai][bj][m][n], 0, 0, 0); } while (0)
; #define PG8_WAIT_V(n) asm volatile("s_waitcnt vmcnt(" #n ")" ::: "memory")
; #define PG8_WAIT_L(n) asm volatile("s_waitcnt lgkmcnt(" #n ")" ::: "memory")
; #define PG8_BAR __builtin_amdgcn_s_barrier()
; #define PG8_SCHED __builtin_amdgcn_sched_barrier(0)
; template <class Prob, class Epi, class Sched>
; __device__ __forceinline__ void gemm_phase(LAS unsigned char* lds, const Prob& P, const Sched& S, const Epi& E) {
;     ...
;             PG8_WAIT_V(8); PG8_WAIT_L(0); PG8_BAR; __builtin_amdgcn_s_setprio(1); PG8_MMA(0, 0, At, B0); PG8_MMA(0, 1, At, B1); __builtin_amdgcn_s_setprio(0); PG8_BAR; PG8_SCHED;
;             PG8_LDA(At, 1, 1); PG8_STAGE(PG8_SB(1, 0), b3, voffB); PG8_STAGE(PG8_SB(1, 1), b3 + hstepB, voffB); PG8_STAGE(PG8_SA(1, 0), a3, voffA);
;             PG8_WAIT_V(8); PG8_WAIT_L(0); PG8_BAR; __builtin_amdgcn_s_setprio(1); PG8_MMA(1, 0, At, B0); PG8_MMA(1, 1, At, B1); __builtin_amdgcn_s_setprio(0); PG8_BAR; PG8_SCHED;
;         }
	v_mfma_f32_16x16x32_bf16 v[2:5], v[130:133], v[182:185], v[2:5]
	v_mfma_f32_16x16x32_bf16 v[18:21], v[138:141], v[182:185], v[18:21]
	v_mfma_f32_16x16x32_bf16 v[26:29], v[130:133], v[190:193], v[26:29]
	v_mfma_f32_16x16x32_bf16 v[38:41], v[138:141], v[190:193], v[38:41]
	v_mfma_f32_16x16x32_bf16 v[6:9], v[130:133], v[198:201], v[6:9]
	v_mfma_f32_16x16x32_bf16 v[14:17], v[138:141], v[198:201], v[14:17]
	v_mfma_f32_16x16x32_bf16 v[10:13], v[130:133], v[206:209], v[10:13]
	v_mfma_f32_16x16x32_bf16 v[22:25], v[138:141], v[206:209], v[22:25]
	v_mfma_f32_16x16x32_bf16 v[62:65], v[148:151], v[182:185], v[62:65]
	v_mfma_f32_16x16x32_bf16 v[94:97], v[174:177], v[182:185], v[94:97]
	v_mfma_f32_16x16x32_bf16 v[30:33], v[148:151], v[190:193], v[30:33]
	v_mfma_f32_16x16x32_bf16 v[46:49], v[174:177], v[190:193], v[46:49]
	v_mfma_f32_16x16x32_bf16 v[34:37], v[148:151], v[198:201], v[34:37]
	v_mfma_f32_16x16x32_bf16 v[54:57], v[174:177], v[198:201], v[54:57]
	v_mfma_f32_16x16x32_bf16 v[42:45], v[148:151], v[206:209], v[42:45]
	v_mfma_f32_16x16x32_bf16 v[58:61], v[174:177], v[206:209], v[58:61]
	v_mfma_f32_16x16x32_bf16 v[2:5], v[134:137], v[186:189], v[2:5]
	v_mfma_f32_16x16x32_bf16 v[18:21], v[142:145], v[186:189], v[18:21]
	v_mfma_f32_16x16x32_bf16 v[26:29], v[134:137], v[194:197], v[26:29]
	v_mfma_f32_16x16x32_bf16 v[38:41], v[142:145], v[194:197], v[38:41]
	v_mfma_f32_16x16x32_bf16 v[6:9], v[134:137], v[202:205], v[6:9]
	v_mfma_f32_16x16x32_bf16 v[14:17], v[142:145], v[202:205], v[14:17]
	v_mfma_f32_16x16x32_bf16 v[10:13], v[134:137], v[210:213], v[10:13]
	v_mfma_f32_16x16x32_bf16 v[22:25], v[142:145], v[210:213], v[22:25]
	v_mfma_f32_16x16x32_bf16 v[62:65], v[164:167], v[186:189], v[62:65]
	v_mfma_f32_16x16x32_bf16 v[94:97], v[178:181], v[186:189], v[94:97]
	v_mfma_f32_16x16x32_bf16 v[30:33], v[164:167], v[194:197], v[30:33]
	v_mfma_f32_16x16x32_bf16 v[46:49], v[178:181], v[194:197], v[46:49]
	v_mfma_f32_16x16x32_bf16 v[34:37], v[164:167], v[202:205], v[34:37]
	v_mfma_f32_16x16x32_bf16 v[54:57], v[178:181], v[202:205], v[54:57]
	v_mfma_f32_16x16x32_bf16 v[42:45], v[164:167], v[210:213], v[42:45]
	v_mfma_f32_16x16x32_bf16 v[58:61], v[178:181], v[210:213], v[58:61]
	s_barrier
	s_setprio 0
	ds_read_b128 v[182:185], v169 offset:49152
	ds_read_b128 v[186:189], v169 offset:50176
	ds_read_b128 v[190:193], v169 offset:51200
	ds_read_b128 v[194:197], v169 offset:52224
	ds_read_b128 v[198:201], v169 offset:53248
	ds_read_b128 v[202:205], v169 offset:54272
	ds_read_b128 v[206:209], v169 offset:55296
	ds_read_b128 v[210:213], v169 offset:56320
	s_add_u32 s42, s40, 0x80
	s_addc_u32 s43, s41, 0
	s_mov_b32 m0, s61
	s_nop 0
	global_load_lds_dwordx4 v159, s[42:43]
	s_nop 1
	s_add_u32 s40, s40, 0x160080
	s_mov_b32 m0, s62
	s_nop 0
	global_load_lds_dwordx4 v163, s[42:43]
	s_nop 1
	s_addc_u32 s41, s41, 0
	s_mov_b32 m0, s65
	s_nop 0
	global_load_lds_dwordx4 v159, s[40:41]
	s_nop 1
	s_nop 0
	s_mov_b32 m0, s66
	s_nop 0
	global_load_lds_dwordx4 v163, s[40:41]
	s_nop 1
	s_nop 0
	s_waitcnt vmcnt(6)
	s_waitcnt lgkmcnt(0)
	s_setprio 1
	s_barrier
	v_mfma_f32_16x16x32_bf16 v[78:81], v[130:133], v[182:185], v[78:81]
	v_mfma_f32_16x16x32_bf16 v[90:93], v[138:141], v[182:185], v[90:93]
	v_mfma_f32_16x16x32_bf16 v[74:77], v[130:133], v[190:193], v[74:77]
	v_mfma_f32_16x16x32_bf16 v[86:89], v[138:141], v[190:193], v[86:89]
	v_mfma_f32_16x16x32_bf16 v[70:73], v[130:133], v[198:201], v[70:73]
	v_mfma_f32_16x16x32_bf16 v[82:85], v[138:141], v[198:201], v[82:85]
	v_mfma_f32_16x16x32_bf16 v[66:69], v[130:133], v[206:209], v[66:69]
	v_mfma_f32_16x16x32_bf16 v[50:53], v[138:141], v[206:209], v[50:53]
	v_mfma_f32_16x16x32_bf16 v[114:117], v[148:151], v[182:185], v[114:117]
	v_mfma_f32_16x16x32_bf16 v[126:129], v[174:177], v[182:185], v[126:129]
	v_mfma_f32_16x16x32_bf16 v[110:113], v[148:151], v[190:193], v[110:113]
	v_mfma_f32_16x16x32_bf16 v[122:125], v[174:177], v[190:193], v[122:125]
	v_mfma_f32_16x16x32_bf16 v[106:109], v[148:151], v[198:201], v[106:109]
	v_mfma_f32_16x16x32_bf16 v[118:121], v[174:177], v[198:201], v[118:121]
	v_mfma_f32_16x16x32_bf16 v[102:105], v[148:151], v[206:209], v[102:105]
	v_mfma_f32_16x16x32_bf16 v[98:101], v[174:177], v[206:209], v[98:101]
	v_mfma_f32_16x16x32_bf16 v[78:81], v[134:137], v[186:189], v[78:81]
	v_mfma_f32_16x16x32_bf16 v[90:93], v[142:145], v[186:189], v[90:93]
	v_mfma_f32_16x16x32_bf16 v[74:77], v[134:137], v[194:197], v[74:77]
	v_mfma_f32_16x16x32_bf16 v[86:89], v[142:145], v[194:197], v[86:89]
	v_mfma_f32_16x16x32_bf16 v[70:73], v[134:137], v[202:205], v[70:73]
	v_mfma_f32_16x16x32_bf16 v[82:85], v[142:145], v[202:205], v[82:85]
	v_mfma_f32_16x16x32_bf16 v[66:69], v[134:137], v[210:213], v[66:69]
	v_mfma_f32_16x16x32_bf16 v[50:53], v[142:145], v[210:213], v[50:53]
	v_mfma_f32_16x16x32_bf16 v[114:117], v[164:167], v[186:189], v[114:117]
	v_mfma_f32_16x16x32_bf16 v[126:129], v[178:181], v[186:189], v[126:129]
	v_mfma_f32_16x16x32_bf16 v[110:113], v[164:167], v[194:197], v[110:113]
	v_mfma_f32_16x16x32_bf16 v[122:125], v[178:181], v[194:197], v[122:125]
	v_mfma_f32_16x16x32_bf16 v[106:109], v[164:167], v[202:205], v[106:109]
	v_mfma_f32_16x16x32_bf16 v[118:121], v[178:181], v[202:205], v[118:121]
	v_mfma_f32_16x16x32_bf16 v[102:105], v[164:167], v[210:213], v[102:105]
	v_mfma_f32_16x16x32_bf16 v[98:101], v[178:181], v[210:213], v[98:101]
	s_barrier
	s_setprio 0
	s_add_i32 s37, s37, 2
	s_add_u32 s4, s4, 0x100
	s_addc_u32 s5, s5, 0
	s_cmpk_gt_u32 s37, 0x55
	s_cbranch_scc0 .LBB0_1159
	s_and_b64 vcc, exec, s[20:21]
	s_cbranch_vccz .LBB0_1162
	s_barrier
